# rg_prompt block 0 conv taps also rebuilt by DPP (one exec-masked 3-row load for the rows before the block) on top of Xb widening
# speedup vs baseline: 1.0160x; 1.0072x over previous
.LBB0_209:
	s_andn2_saveexec_b64 s[54:55], s[80:81]
	v_fma_f32 v82, v81, s92, 0.5
	v_fma_f32 v82, -v81, v82, 1.0
	v_mul_f32_e32 v170, v81, v82
	s_or_b64 exec, exec, s[54:55]
	v_lshl_add_u64 v[138:139], s[74:75], 0, v[118:119]
	v_add_co_u32_e32 v84, vcc, 0x13094000, v138
	v_max_f32_e64 v76, -v76, -v76
	s_nop 0
	v_addc_co_u32_e32 v85, vcc, 0, v139, vcc
	s_nop 0
	v_add_co_u32_e32 v84, vcc, 0x13098000, v138
	v_max_f32_e32 v76, 0, v76
	s_nop 0
	v_addc_co_u32_e32 v85, vcc, 0, v139, vcc
	s_nop 0
	v_add_co_u32_e32 v84, vcc, 0x1309c000, v138
	v_add_f32_e32 v185, v76, v80
	s_nop 0
	v_addc_co_u32_e32 v85, vcc, 0, v139, vcc
	v_add_co_u32_e32 v140, vcc, 0x130a1000, v138
	s_nop 0
	s_nop 0
	v_addc_co_u32_e32 v141, vcc, 0, v139, vcc
	s_mov_b32 s100, 0x1305f000
	s_mov_b32 s101, 0
	v_lshl_add_u64 v[248:249], v[138:139], 0, s[100:101]
	s_mov_b32 exec_lo, 0xe000e000
	s_mov_b32 exec_hi, 0xe000e000
	global_load_dwordx2 v[168:169], v[248:249], off
	s_mov_b64 exec, -1
	global_load_dwordx2 v[166:167], v[140:141], off
	global_load_dwordx2 v[142:143], v[140:141], off offset:2048
	v_add_co_u32_e32 v140, vcc, s97, v138
	v_mfma_f32_16x16x32_bf16 v[84:87], v[72:75], v[0:3], 0
	s_nop 0
	v_addc_co_u32_e32 v141, vcc, 0, v139, vcc
	global_load_dwordx2 v[140:141], v[140:141], off
	s_nop 0
	s_nop 0
	s_nop 0
	s_mov_b32 s100, 0x130e3000
	s_mov_b32 s101, 0
	v_lshl_add_u64 v[248:249], v[138:139], 0, s[100:101]
	global_load_dwordx2 v[216:217], v[248:249], off
	s_mov_b32 s100, 0x130e3800
	s_mov_b32 s101, 0
	v_lshl_add_u64 v[248:249], v[138:139], 0, s[100:101]
	global_load_dwordx2 v[218:219], v[248:249], off
	s_mov_b32 s100, 0x130e6000
	s_mov_b32 s101, 0
	v_lshl_add_u64 v[248:249], v[138:139], 0, s[100:101]
	global_load_dwordx2 v[220:221], v[248:249], off
	s_nop 0
	s_nop 0
	s_nop 0
	s_mov_b32 s100, 0x13125000
	s_mov_b32 s101, 0
	v_lshl_add_u64 v[248:249], v[138:139], 0, s[100:101]
	global_load_dwordx2 v[228:229], v[248:249], off
	s_mov_b32 s100, 0x13125800
	s_mov_b32 s101, 0
	v_lshl_add_u64 v[248:249], v[138:139], 0, s[100:101]
	global_load_dwordx2 v[230:231], v[248:249], off
	s_mov_b32 s100, 0x13128000
	s_mov_b32 s101, 0
	v_lshl_add_u64 v[248:249], v[138:139], 0, s[100:101]
	global_load_dwordx2 v[232:233], v[248:249], off
	s_nop 0
	s_nop 0
	s_nop 0
	s_mov_b32 s100, 0x13167000
	s_mov_b32 s101, 0
	v_lshl_add_u64 v[248:249], v[138:139], 0, s[100:101]
	global_load_dwordx2 v[242:243], v[248:249], off
	s_mov_b32 s100, 0x13167800
	s_mov_b32 s101, 0
	v_lshl_add_u64 v[248:249], v[138:139], 0, s[100:101]
	global_load_dwordx2 v[244:245], v[248:249], off
	s_mov_b32 s100, 0x1316a000
	s_mov_b32 s101, 0
	v_lshl_add_u64 v[248:249], v[138:139], 0, s[100:101]
	global_load_dwordx2 v[246:247], v[248:249], off
	v_mfma_f32_16x16x32_bf16 v[84:87], v[60:63], v[16:19], v[84:87]
	v_mfma_f32_16x16x32_bf16 v[80:83], v[68:71], v[0:3], 0
	v_mfma_f32_16x16x32_bf16 v[80:83], v[64:67], v[16:19], v[80:83]
	s_nop 0
	s_nop 4
	s_nop 0
	s_waitcnt vmcnt(14)
	v_add_f32_e32 v76, v56, v84
	v_mul_f32_e32 v76, 0xbfb8aa3b, v76
	v_exp_f32_e32 v76, v76
	s_nop 0
	v_add_f32_e32 v76, 1.0, v76
	v_rcp_f32_e32 v76, v76
	s_nop 0
	v_mul_f32_e32 v76, 0xc1000000, v76
	v_mul_f32_e32 v76, v185, v76
	v_add_f32_e32 v171, v76, v76
	v_cmp_nlt_f32_e32 vcc, s93, v171
	s_and_saveexec_b64 s[54:55], vcc
	s_xor_b64 s[54:55], exec, s[54:55]
	v_mul_f32_e32 v84, 0x3fb8aa3b, v171
	v_exp_f32_e32 v84, v84
	s_nop 0
	v_sub_f32_e32 v84, 1.0, v84
	s_andn2_saveexec_b64 s[54:55], s[54:55]
	v_fma_f32 v84, v171, s94, 0.5
	v_fma_f32 v84, v171, v84, 1.0
	v_mul_f32_e64 v84, v84, -v171
	s_or_b64 exec, exec, s[54:55]
	v_add_f32_e32 v85, v57, v85
	v_mul_f32_e32 v85, 0xbfb8aa3b, v85
	v_exp_f32_e32 v85, v85
	v_max_f32_e64 v77, -v77, -v77
	v_max_f32_e32 v77, 0, v77
	v_add_f32_e32 v186, v77, v144
	v_add_f32_e32 v85, 1.0, v85
	v_rcp_f32_e32 v85, v85
	s_nop 0
	v_mul_f32_e32 v77, 0xc1000000, v85
	v_mul_f32_e32 v77, v186, v77
	v_add_f32_e32 v144, v77, v77
	v_cmp_nlt_f32_e32 vcc, s93, v144
	s_and_saveexec_b64 s[54:55], vcc
	s_xor_b64 s[54:55], exec, s[54:55]
	v_mul_f32_e32 v85, 0x3fb8aa3b, v144
	v_exp_f32_e32 v85, v85
	s_nop 0
	v_sub_f32_e32 v85, 1.0, v85
	s_andn2_saveexec_b64 s[54:55], s[54:55]
	v_fma_f32 v85, v144, s94, 0.5
	v_fma_f32 v85, v144, v85, 1.0
	v_mul_f32_e64 v85, v85, -v144
	s_or_b64 exec, exec, s[54:55]
	v_add_f32_e32 v86, v58, v86
	v_mul_f32_e32 v86, 0xbfb8aa3b, v86
	v_exp_f32_e32 v86, v86
	v_max_f32_e64 v78, -v78, -v78
	v_max_f32_e32 v78, 0, v78
	v_add_f32_e32 v187, v78, v147
	v_add_f32_e32 v86, 1.0, v86
	v_rcp_f32_e32 v86, v86
	s_nop 0
	v_mul_f32_e32 v78, 0xc1000000, v86
	v_mul_f32_e32 v78, v187, v78
	v_add_f32_e32 v144, v78, v78
	v_cmp_nlt_f32_e32 vcc, s93, v144
	s_and_saveexec_b64 s[54:55], vcc
	s_xor_b64 s[54:55], exec, s[54:55]
	v_mul_f32_e32 v86, 0x3fb8aa3b, v144
	v_exp_f32_e32 v86, v86
	s_nop 0
	v_sub_f32_e32 v86, 1.0, v86
	s_andn2_saveexec_b64 s[54:55], s[54:55]
	v_fma_f32 v86, v144, s94, 0.5
	v_fma_f32 v86, v144, v86, 1.0
	v_mul_f32_e64 v86, v86, -v144
	s_or_b64 exec, exec, s[54:55]
	v_add_f32_e32 v87, v59, v87
	v_mul_f32_e32 v87, 0xbfb8aa3b, v87
	v_exp_f32_e32 v87, v87
	v_max_f32_e64 v79, -v79, -v79
	v_max_f32_e32 v79, 0, v79
	v_add_f32_e32 v188, v79, v170
	v_add_f32_e32 v87, 1.0, v87
	v_rcp_f32_e32 v87, v87
	s_nop 0
	v_mul_f32_e32 v79, 0xc1000000, v87
	v_mul_f32_e32 v87, v188, v79
	v_add_f32_e32 v144, v87, v87
	v_cmp_nlt_f32_e32 vcc, s93, v144
	s_and_saveexec_b64 s[54:55], vcc
	s_xor_b64 s[54:55], exec, s[54:55]
	v_mul_f32_e32 v79, 0x3fb8aa3b, v144
	v_exp_f32_e32 v79, v79
	s_nop 0
	v_sub_f32_e32 v79, 1.0, v79
	s_andn2_saveexec_b64 s[54:55], s[54:55]
	v_fma_f32 v79, v144, s94, 0.5
	v_fma_f32 v79, v144, v79, 1.0
	v_mul_f32_e64 v79, v79, -v144
	s_or_b64 exec, exec, s[54:55]
	s_nop 0
	s_nop 0
	s_waitcnt vmcnt(13)
	v_add_f32_e32 v82, v34, v82
	v_mul_f32_e32 v82, 0xbfb8aa3b, v82
	v_exp_f32_e32 v82, v82
	v_add_f32_e32 v81, v33, v81
	s_nop 0
	s_nop 0
	s_waitcnt vmcnt(12)
	v_mov_b32_dpp v164, v168 row_shl:14 row_mask:0xf bank_mask:0xf
	v_mov_b32_dpp v165, v169 row_shl:14 row_mask:0xf bank_mask:0xf
	v_mov_b32_dpp v162, v168 row_shl:15 row_mask:0xf bank_mask:0xf
	v_mov_b32_dpp v163, v169 row_shl:15 row_mask:0xf bank_mask:0xf
	v_mov_b32_dpp v168, v168 row_shl:13 row_mask:0xf bank_mask:0xf
	v_mov_b32_dpp v169, v169 row_shl:13 row_mask:0xf bank_mask:0xf
	s_waitcnt vmcnt(11)
	v_mov_b32_dpp v168, v166 row_shr:3 row_mask:0xf bank_mask:0xf
	v_mov_b32_dpp v169, v167 row_shr:3 row_mask:0xf bank_mask:0xf
	v_mov_b32_dpp v164, v166 row_shr:2 row_mask:0xf bank_mask:0xf
	v_mov_b32_dpp v165, v167 row_shr:2 row_mask:0xf bank_mask:0xf
	v_mov_b32_dpp v162, v166 row_shr:1 row_mask:0xf bank_mask:0xf
	v_mov_b32_dpp v163, v167 row_shr:1 row_mask:0xf bank_mask:0xf
	v_cndmask_b32_e64 v144, v169, 0, s[28:29]
	v_cndmask_b32_e64 v147, v168, 0, s[28:29]
	v_add_f32_e32 v82, 1.0, v82
	v_add_f32_e32 v83, v35, v83
	v_mul_f32_e32 v81, 0xbfb8aa3b, v81
	v_lshlrev_b32_e32 v152, 16, v147
	v_and_b32_e32 v153, 0xffff0000, v147
	v_lshlrev_b32_e32 v168, 16, v144
	v_and_b32_e32 v169, 0xffff0000, v144
	s_nop 0
	s_nop 0
	v_cndmask_b32_e64 v144, v165, 0, s[30:31]
	v_cndmask_b32_e64 v147, v164, 0, s[30:31]
	v_rcp_f32_e32 v82, v82
	v_sqrt_f32_e32 v86, v86
	v_mul_f32_e32 v83, 0xbfb8aa3b, v83
	v_exp_f32_e32 v81, v81
	v_pk_fma_f32 v[168:169], v[50:51], v[168:169], v[54:55]
	v_pk_fma_f32 v[152:153], v[48:49], v[152:153], v[52:53]
	v_lshlrev_b32_e32 v164, 16, v147
	v_and_b32_e32 v165, 0xffff0000, v147
	v_lshlrev_b32_e32 v170, 16, v144
	v_and_b32_e32 v171, 0xffff0000, v144
	s_nop 0
	s_nop 0
	v_cndmask_b32_e64 v144, v163, 0, s[34:35]
	v_cndmask_b32_e64 v147, v162, 0, s[34:35]
	v_exp_f32_e32 v83, v83
	v_pk_fma_f32 v[152:153], v[44:45], v[164:165], v[152:153]
	v_pk_fma_f32 v[164:165], v[46:47], v[170:171], v[168:169]
	v_lshlrev_b32_e32 v162, 16, v147
	v_and_b32_e32 v163, 0xffff0000, v147
	v_lshlrev_b32_e32 v168, 16, v144
	v_and_b32_e32 v169, 0xffff0000, v144
	s_nop 0
	s_nop 0
	v_mov_b32_dpp v194, v166 row_shl:13 row_mask:0xf bank_mask:0xf
	v_mov_b32_dpp v195, v167 row_shl:13 row_mask:0xf bank_mask:0xf
	v_mov_b32_dpp v212, v166 row_shl:14 row_mask:0xf bank_mask:0xf
	v_mov_b32_dpp v213, v167 row_shl:14 row_mask:0xf bank_mask:0xf
	v_mov_b32_dpp v214, v166 row_shl:15 row_mask:0xf bank_mask:0xf
	v_mov_b32_dpp v215, v167 row_shl:15 row_mask:0xf bank_mask:0xf
	v_cndmask_b32_e64 v144, v167, 0, s[64:65]
	v_cndmask_b32_e64 v147, v166, 0, s[64:65]
	v_add_f32_e32 v80, v32, v80
	v_pk_fma_f32 v[164:165], v[42:43], v[168:169], v[164:165]
	v_pk_fma_f32 v[152:153], v[40:41], v[162:163], v[152:153]
	v_lshlrev_b32_e32 v162, 16, v147
	v_and_b32_e32 v163, 0xffff0000, v147
	v_lshlrev_b32_e32 v166, 16, v144
	v_and_b32_e32 v167, 0xffff0000, v144
	v_mul_f32_e32 v80, 0xbfb8aa3b, v80
	v_pk_fma_f32 v[152:153], v[36:37], v[162:163], v[152:153]
	v_pk_fma_f32 v[162:163], v[38:39], v[166:167], v[164:165]
	v_mul_f32_e32 v82, v82, v86
	v_add_f32_e32 v81, 1.0, v81
	v_exp_f32_e32 v80, v80
	v_mul_f32_e32 v162, v162, v82
	v_add_f32_e32 v82, 1.0, v83
	v_rcp_f32_e32 v81, v81
	v_sqrt_f32_e32 v83, v85
	v_add_f32_e32 v80, 1.0, v80
	v_rcp_f32_e32 v80, v80
	v_mul_f32_e32 v76, 0x3fb8aa3b, v76
	v_mul_f32_e32 v81, v81, v83
	v_sqrt_f32_e32 v83, v84
	v_exp_f32_e32 v76, v76
	v_mul_f32_e32 v77, 0x3fb8aa3b, v77
	v_mul_f32_e32 v85, 0x3fb8aa3b, v87
	v_mul_f32_e32 v80, v80, v83
	v_mul_f32_e32 v87, v152, v80
	v_exp_f32_e32 v77, v77
	v_mov_b32_e32 v80, 0
	v_rcp_f32_e32 v82, v82
	v_mul_f32_e32 v78, 0x3fb8aa3b, v78
	v_sqrt_f32_e32 v79, v79
	v_mov_b32_dpp v80, v87 row_shr:1 row_mask:0xf bank_mask:0xf
	v_mul_f32_e32 v153, v153, v81
	v_exp_f32_e32 v78, v78
	v_fmac_f32_e32 v87, v76, v80
	v_mov_b32_e32 v80, 0
	v_exp_f32_e32 v85, v85
	v_mul_f32_e32 v79, v82, v79
	v_mov_b32_dpp v80, v153 row_shr:1 row_mask:0xf bank_mask:0xf
	v_fmac_f32_e32 v153, v77, v80
	v_mov_b32_e32 v80, 0
	v_mul_f32_e32 v152, v163, v79
	v_mov_b32_e32 v79, 1.0
	v_mov_b32_dpp v80, v162 row_shr:1 row_mask:0xf bank_mask:0xf
	v_fmac_f32_e32 v162, v78, v80
	v_mov_b32_e32 v80, 0
	v_mov_b32_dpp v79, v76 row_shr:1 row_mask:0xf bank_mask:0xf
	v_mul_f32_e32 v76, v76, v79
	v_mov_b32_dpp v80, v152 row_shr:1 row_mask:0xf bank_mask:0xf
	v_mov_b32_e32 v79, 1.0
	v_fmac_f32_e32 v152, v85, v80
	v_mov_b32_e32 v80, 1.0
	v_mov_b32_e32 v81, 0
	v_mov_b32_dpp v79, v77 row_shr:1 row_mask:0xf bank_mask:0xf
	v_mov_b32_dpp v80, v76 row_shr:2 row_mask:0xf bank_mask:0xf
	v_mov_b32_dpp v81, v87 row_shr:2 row_mask:0xf bank_mask:0xf
	v_mul_f32_e32 v77, v77, v79
	v_mov_b32_e32 v79, 1.0
	v_fmac_f32_e32 v87, v76, v81
	v_mul_f32_e32 v147, v76, v80
	v_mov_b32_e32 v76, 1.0
	v_mov_b32_dpp v79, v78 row_shr:1 row_mask:0xf bank_mask:0xf
	v_mul_f32_e32 v78, v78, v79
	v_mov_b32_dpp v76, v77 row_shr:2 row_mask:0xf bank_mask:0xf
	v_mov_b32_e32 v79, 1.0
	v_mul_f32_e32 v163, v77, v76
	v_mov_b32_e32 v76, 1.0
	v_mov_b32_dpp v79, v85 row_shr:1 row_mask:0xf bank_mask:0xf
	v_mul_f32_e32 v79, v85, v79
	v_mov_b32_dpp v76, v78 row_shr:2 row_mask:0xf bank_mask:0xf
	v_mul_f32_e32 v164, v78, v76
	v_mov_b32_e32 v76, 1.0
	v_mov_b32_e32 v80, 0
	s_nop 0
	s_nop 0
	s_waitcnt vmcnt(9)
	v_lshlrev_b32_e32 v84, 16, v140
	v_mov_b32_dpp v76, v79 row_shr:2 row_mask:0xf bank_mask:0xf
	v_mul_f32_e32 v165, v79, v76
	v_mov_b32_e32 v76, 0
	v_mov_b32_dpp v80, v153 row_shr:2 row_mask:0xf bank_mask:0xf
	v_fmac_f32_e32 v153, v77, v80
	v_mov_b32_dpp v76, v87 row_shr:4 row_mask:0xf bank_mask:0xf
	v_mov_b32_e32 v77, 0
	v_fmac_f32_e32 v87, v147, v76
	v_mov_b32_e32 v76, 0
	v_mov_b32_dpp v77, v162 row_shr:2 row_mask:0xf bank_mask:0xf
	v_fmac_f32_e32 v162, v78, v77
	v_mov_b32_dpp v76, v153 row_shr:4 row_mask:0xf bank_mask:0xf
	v_mov_b32_e32 v77, 0
	v_fmac_f32_e32 v153, v163, v76
	v_mov_b32_e32 v76, 0
	v_mov_b32_dpp v77, v152 row_shr:2 row_mask:0xf bank_mask:0xf
	v_fmac_f32_e32 v152, v79, v77
	v_mov_b32_dpp v76, v162 row_shr:4 row_mask:0xf bank_mask:0xf
	v_fmac_f32_e32 v162, v164, v76
	v_mov_b32_e32 v76, 0
	v_mov_b32_e32 v77, 1.0
	v_mul_f32_e32 v84, 0xbfb8aa3b, v84
	v_mov_b32_dpp v76, v152 row_shr:4 row_mask:0xf bank_mask:0xf
	v_mov_b32_dpp v77, v147 row_shr:4 row_mask:0xf bank_mask:0xf
	v_fmac_f32_e32 v152, v165, v76
	v_lshlrev_b32_e32 v76, 16, v142
	v_and_b32_e32 v78, 0xffff0000, v142
	v_and_b32_e32 v142, 0xffff0000, v140
	v_exp_f32_e32 v140, v84
	v_pk_mul_f32 v[84:85], v[146:147], v[76:77]
	v_mul_f32_e32 v77, 0x3d372713, v76
	v_mul_f32_e32 v77, v77, v76
	v_fmac_f32_e32 v76, v77, v76
	v_mul_f32_e32 v76, 0x3f4c422a, v76
	v_add_f32_e32 v76, v76, v76
	v_mul_f32_e32 v76, 0x3fb8aa3b, v76
	v_exp_f32_e32 v76, v76
	v_add_f32_e32 v77, 1.0, v140
	v_rcp_f32_e32 v144, v77
	v_mov_b32_e32 v77, 1.0
	v_add_f32_e32 v76, 1.0, v76
	v_rcp_f32_e32 v76, v76
	v_mov_b32_e32 v86, 0
	v_mov_b32_dpp v77, v85 row_shr:8 row_mask:0xf bank_mask:0xf
	v_mov_b32_e32 v79, 1.0
	v_fma_f32 v76, v76, -2.0, 1.0
	v_add_f32_e32 v76, 1.0, v76
	v_mov_b32_dpp v86, v87 row_shr:8 row_mask:0xf bank_mask:0xf
	v_pk_mul_f32 v[76:77], v[84:85], v[76:77]
	v_lshlrev_b32_e32 v169, 16, v141
	v_and_b32_e32 v170, 0xffff0000, v141
	v_fmac_f32_e32 v87, v85, v86
	v_pk_mul_f32 v[140:141], v[144:145], v[76:77]
	v_mov_b32_dpp v79, v163 row_shr:4 row_mask:0xf bank_mask:0xf
	v_add_f32_e32 v76, v141, v87
	v_mov_b32_e32 v147, v163
	v_lshlrev_b32_e32 v80, 16, v143
	v_and_b32_e32 v82, 0xffff0000, v143
	v_mul_f32_e32 v171, v140, v76
	v_mul_f32_e32 v76, 0xbfb8aa3b, v142
	v_pk_mul_f32 v[142:143], v[146:147], v[78:79]
	v_mul_f32_e32 v79, 0x3d372713, v78
	v_mul_f32_e32 v79, v79, v78
	v_fmac_f32_e32 v78, v79, v78
	v_mul_f32_e32 v78, 0x3f4c422a, v78
	v_add_f32_e32 v78, v78, v78
	v_exp_f32_e32 v76, v76
	v_mul_f32_e32 v78, 0x3fb8aa3b, v78
	v_exp_f32_e32 v78, v78
	ds_bpermute_b32 v86, v184, v77
	v_add_f32_e32 v76, 1.0, v76
	v_rcp_f32_e32 v144, v76
	v_add_f32_e32 v76, 1.0, v78
	v_rcp_f32_e32 v76, v76
	v_mul_f32_e32 v163, v140, v77
	v_mov_b32_e32 v77, 1.0
	v_mov_b32_e32 v166, 0
	v_fma_f32 v76, v76, -2.0, 1.0
	v_mov_b32_dpp v77, v143 row_shr:8 row_mask:0xf bank_mask:0xf
	v_add_f32_e32 v76, 1.0, v76
	v_mov_b32_dpp v166, v153 row_shr:8 row_mask:0xf bank_mask:0xf
	v_pk_mul_f32 v[76:77], v[142:143], v[76:77]
	v_fmac_f32_e32 v153, v143, v166
	v_pk_mul_f32 v[78:79], v[144:145], v[76:77]
	v_mov_b32_e32 v81, 1.0
	v_add_f32_e32 v76, v79, v153
	v_mul_f32_e32 v79, 0x3d372713, v80
	v_mov_b32_dpp v81, v164 row_shr:4 row_mask:0xf bank_mask:0xf
	v_mov_b32_e32 v147, v164
	v_mul_f32_e32 v79, v79, v80
	v_pk_mul_f32 v[140:141], v[146:147], v[80:81]
	v_fmac_f32_e32 v80, v79, v80
	v_mul_f32_e32 v79, 0x3f4c422a, v80
	ds_bpermute_b32 v85, v184, v153
	v_mul_f32_e32 v153, v78, v76
	v_mul_f32_e32 v76, 0xbfb8aa3b, v169
	v_add_f32_e32 v79, v79, v79
	v_exp_f32_e32 v76, v76
	v_mul_f32_e32 v79, 0x3fb8aa3b, v79
	v_exp_f32_e32 v79, v79
	ds_bpermute_b32 v84, v184, v87
	v_add_f32_e32 v76, 1.0, v76
	v_rcp_f32_e32 v144, v76
	v_add_f32_e32 v76, 1.0, v79
	v_rcp_f32_e32 v76, v76
	ds_bpermute_b32 v87, v184, v77
	v_mul_f32_e32 v164, v78, v77
	v_mov_b32_e32 v77, 1.0
	v_fma_f32 v76, v76, -2.0, 1.0
	v_mov_b32_e32 v167, 0
	v_mov_b32_dpp v77, v141 row_shr:8 row_mask:0xf bank_mask:0xf
	v_add_f32_e32 v76, 1.0, v76
	v_mov_b32_dpp v167, v162 row_shr:8 row_mask:0xf bank_mask:0xf
	v_pk_mul_f32 v[76:77], v[140:141], v[76:77]
	v_fmac_f32_e32 v162, v141, v167
	v_pk_mul_f32 v[78:79], v[144:145], v[76:77]
	v_mov_b32_e32 v83, 1.0
	v_add_f32_e32 v76, v79, v162
	v_mul_f32_e32 v79, 0x3d372713, v82
	v_mov_b32_dpp v83, v165 row_shr:4 row_mask:0xf bank_mask:0xf
	v_mov_b32_e32 v147, v165
	v_mul_f32_e32 v79, v79, v82
	v_pk_mul_f32 v[80:81], v[146:147], v[82:83]
	v_fmac_f32_e32 v82, v79, v82
	v_mul_f32_e32 v79, 0x3f4c422a, v82
	ds_bpermute_b32 v142, v184, v162
	v_mul_f32_e32 v162, v78, v76
	v_mul_f32_e32 v76, 0xbfb8aa3b, v170
	v_add_f32_e32 v79, v79, v79
	v_exp_f32_e32 v76, v76
	v_mul_f32_e32 v79, 0x3fb8aa3b, v79
	v_exp_f32_e32 v79, v79
	ds_bpermute_b32 v140, v184, v77
	v_add_f32_e32 v76, 1.0, v76
	v_rcp_f32_e32 v144, v76
	v_add_f32_e32 v76, 1.0, v79
	v_rcp_f32_e32 v76, v76
	v_mul_f32_e32 v82, v78, v77
	v_mov_b32_e32 v77, 1.0
	v_mov_b32_e32 v168, 0
	v_fma_f32 v76, v76, -2.0, 1.0
	v_mov_b32_dpp v77, v81 row_shr:8 row_mask:0xf bank_mask:0xf
	v_add_f32_e32 v76, 1.0, v76
	v_mov_b32_dpp v168, v152 row_shr:8 row_mask:0xf bank_mask:0xf
	v_pk_mul_f32 v[76:77], v[80:81], v[76:77]
	v_fmac_f32_e32 v152, v81, v168
	v_pk_mul_f32 v[78:79], v[144:145], v[76:77]
	ds_bpermute_b32 v141, v184, v77
	v_add_f32_e32 v76, v79, v152
	v_mul_f32_e32 v79, v78, v76
	ds_bpermute_b32 v143, v184, v152
	v_mul_f32_e32 v83, v78, v77
	v_cvt_pk_bf16_f32 v77, v162, v79
	v_lshl_add_u64 v[78:79], s[74:75], 0, v[134:135]
	v_add_co_u32_e32 v80, vcc, s95, v78
	v_cvt_pk_bf16_f32 v76, v171, v153
	s_nop 1
	v_addc_co_u32_e32 v81, vcc, 0, v79, vcc
	v_add_co_u32_e32 v78, vcc, s96, v78
	global_store_dwordx2 v[80:81], v[76:77], off
	s_nop 0
	v_addc_co_u32_e32 v79, vcc, 0, v79, vcc
	v_cvt_pk_bf16_f32 v76, v163, v164
	v_cvt_pk_bf16_f32 v77, v82, v83
	global_store_dwordx2 v[78:79], v[76:77], off
	s_mov_b32 s54, 0x130d6000
	v_add_co_u32_e32 v80, vcc, s54, v138
	s_mov_b32 s54, 0x130da000
	s_nop 0
	v_addc_co_u32_e32 v81, vcc, 0, v139, vcc
	s_nop 0
	v_add_co_u32_e32 v80, vcc, s54, v138
	s_mov_b32 s54, 0x130de000
	s_nop 0
	v_addc_co_u32_e32 v81, vcc, 0, v139, vcc
	s_nop 0
	v_add_co_u32_e32 v80, vcc, s54, v138
	s_mov_b32 s54, 0x130e3000
	s_nop 0
	v_addc_co_u32_e32 v81, vcc, 0, v139, vcc
	v_add_co_u32_e32 v152, vcc, s54, v138
	s_nop 0
	s_nop 0
	v_addc_co_u32_e32 v153, vcc, 0, v139, vcc
	s_nop 0
	s_nop 0
	v_add_co_u32_e32 v152, vcc, 0x130e6000, v138
	v_mfma_f32_16x16x32_bf16 v[80:83], v[72:75], v[4:7], 0
	s_nop 0
	v_addc_co_u32_e32 v153, vcc, 0, v139, vcc
	s_nop 0
	v_mfma_f32_16x16x32_bf16 v[80:83], v[60:63], v[20:23], v[80:83]
	v_mfma_f32_16x16x32_bf16 v[76:79], v[68:71], v[4:7], 0
	v_mfma_f32_16x16x32_bf16 v[76:79], v[64:67], v[20:23], v[76:79]
	s_nop 5
	v_add_f32_e32 v80, v56, v80
	v_mul_f32_e32 v80, 0xbfb8aa3b, v80
	v_exp_f32_e32 v80, v80
	s_nop 0
	v_add_f32_e32 v80, 1.0, v80
	v_rcp_f32_e32 v80, v80
	s_nop 0
	v_mul_f32_e32 v80, 0xc1000000, v80
	v_mul_f32_e32 v80, v185, v80
	v_add_f32_e32 v147, v80, v80
	v_cmp_nlt_f32_e32 vcc, s93, v147
	s_and_saveexec_b64 s[54:55], vcc
	s_xor_b64 s[54:55], exec, s[54:55]
	v_mul_f32_e32 v144, 0x3fb8aa3b, v147
	v_exp_f32_e32 v144, v144
	s_nop 0
	v_sub_f32_e32 v144, 1.0, v144
	s_andn2_saveexec_b64 s[54:55], s[54:55]
	v_fma_f32 v144, v147, s94, 0.5
	v_fma_f32 v144, v147, v144, 1.0
	v_mul_f32_e64 v144, v144, -v147
	s_or_b64 exec, exec, s[54:55]
	v_add_f32_e32 v81, v57, v81
	v_mul_f32_e32 v81, 0xbfb8aa3b, v81
	v_exp_f32_e32 v81, v81
	s_nop 0
	v_add_f32_e32 v81, 1.0, v81
	v_rcp_f32_e32 v81, v81
	s_nop 0
	v_mul_f32_e32 v81, 0xc1000000, v81
	v_mul_f32_e32 v81, v186, v81
	v_add_f32_e32 v174, v81, v81
	v_cmp_nlt_f32_e32 vcc, s93, v174
	s_and_saveexec_b64 s[54:55], vcc
	s_xor_b64 s[54:55], exec, s[54:55]
	v_mul_f32_e32 v147, 0x3fb8aa3b, v174
	v_exp_f32_e32 v147, v147
	s_nop 0
	v_sub_f32_e32 v147, 1.0, v147
	s_andn2_saveexec_b64 s[54:55], s[54:55]
	v_fma_f32 v147, v174, s94, 0.5
	v_fma_f32 v147, v174, v147, 1.0
	v_mul_f32_e64 v147, v147, -v174
	s_or_b64 exec, exec, s[54:55]
	v_add_f32_e32 v82, v58, v82
	v_mul_f32_e32 v82, 0xbfb8aa3b, v82
	v_exp_f32_e32 v82, v82
	s_nop 0
	v_add_f32_e32 v82, 1.0, v82
	v_rcp_f32_e32 v82, v82
	s_nop 0
	v_mul_f32_e32 v82, 0xc1000000, v82
	v_mul_f32_e32 v82, v187, v82
	v_add_f32_e32 v175, v82, v82
	v_cmp_nlt_f32_e32 vcc, s93, v175
	s_and_saveexec_b64 s[54:55], vcc
	s_xor_b64 s[54:55], exec, s[54:55]
	v_mul_f32_e32 v152, 0x3fb8aa3b, v175
	v_exp_f32_e32 v152, v152
	s_nop 0
	v_sub_f32_e32 v174, 1.0, v152
	s_andn2_saveexec_b64 s[54:55], s[54:55]
	v_fma_f32 v152, v175, s94, 0.5
	v_fma_f32 v152, v175, v152, 1.0
	v_mul_f32_e64 v174, v152, -v175
	s_or_b64 exec, exec, s[54:55]
	v_add_f32_e32 v83, v59, v83
	v_mul_f32_e32 v83, 0xbfb8aa3b, v83
	v_exp_f32_e32 v83, v83
	s_nop 0
	v_add_f32_e32 v83, 1.0, v83
	v_rcp_f32_e32 v83, v83
	s_nop 0
	v_mul_f32_e32 v83, 0xc1000000, v83
	v_mul_f32_e32 v175, v188, v83
	v_add_f32_e32 v176, v175, v175
	v_cmp_nlt_f32_e32 vcc, s93, v176
	s_and_saveexec_b64 s[54:55], vcc
	s_xor_b64 s[54:55], exec, s[54:55]
	v_mul_f32_e32 v83, 0x3fb8aa3b, v176
	v_exp_f32_e32 v83, v83
	s_nop 0
	v_sub_f32_e32 v83, 1.0, v83
	s_andn2_saveexec_b64 s[54:55], s[54:55]
	v_fma_f32 v83, v176, s94, 0.5
	v_fma_f32 v83, v176, v83, 1.0
	v_mul_f32_e64 v83, v83, -v176
	s_or_b64 exec, exec, s[54:55]
	v_add_f32_e32 v78, v34, v78
	v_mul_f32_e32 v78, 0xbfb8aa3b, v78
	s_nop 0
	s_nop 0
	s_waitcnt vmcnt(10)
	v_mov_b32_dpp v194, v216 row_shr:3 row_mask:0xf bank_mask:0xf
	v_mov_b32_dpp v195, v217 row_shr:3 row_mask:0xf bank_mask:0xf
	v_mov_b32_dpp v212, v216 row_shr:2 row_mask:0xf bank_mask:0xf
	v_mov_b32_dpp v213, v217 row_shr:2 row_mask:0xf bank_mask:0xf
	v_mov_b32_dpp v214, v216 row_shr:1 row_mask:0xf bank_mask:0xf
	v_mov_b32_dpp v215, v217 row_shr:1 row_mask:0xf bank_mask:0xf
	v_cndmask_b32_e64 v171, v195, 0, s[36:37]
	v_cndmask_b32_e64 v153, v194, 0, s[36:37]
	v_exp_f32_e32 v78, v78
	v_lshlrev_b32_e32 v152, 16, v153
	v_and_b32_e32 v153, 0xffff0000, v153
	v_lshlrev_b32_e32 v170, 16, v171
	v_and_b32_e32 v171, 0xffff0000, v171
	s_nop 0
	s_nop 0
	v_cndmask_b32_e64 v177, v213, 0, s[38:39]
	v_cndmask_b32_e64 v163, v212, 0, s[38:39]
	v_pk_fma_f32 v[170:171], v[50:51], v[170:171], v[54:55]
	v_pk_fma_f32 v[152:153], v[48:49], v[152:153], v[52:53]
	v_lshlrev_b32_e32 v162, 16, v163
	v_and_b32_e32 v163, 0xffff0000, v163
	v_lshlrev_b32_e32 v176, 16, v177
	v_and_b32_e32 v177, 0xffff0000, v177
	v_pk_fma_f32 v[152:153], v[44:45], v[162:163], v[152:153]
	v_pk_fma_f32 v[162:163], v[46:47], v[176:177], v[170:171]
	s_nop 0
	s_nop 0
	v_cndmask_b32_e64 v171, v215, 0, s[40:41]
	v_cndmask_b32_e64 v169, v214, 0, s[40:41]
	v_add_f32_e32 v77, v33, v77
	v_lshlrev_b32_e32 v168, 16, v169
	v_and_b32_e32 v169, 0xffff0000, v169
	v_add_f32_e32 v78, 1.0, v78
	v_add_f32_e32 v79, v35, v79
	v_mul_f32_e32 v77, 0xbfb8aa3b, v77
	v_pk_fma_f32 v[152:153], v[40:41], v[168:169], v[152:153]
	s_nop 0
	s_nop 0
	v_mov_b32_dpp v222, v216 row_shl:13 row_mask:0xf bank_mask:0xf
	v_mov_b32_dpp v223, v217 row_shl:13 row_mask:0xf bank_mask:0xf
	v_mov_b32_dpp v224, v216 row_shl:14 row_mask:0xf bank_mask:0xf
	v_mov_b32_dpp v225, v217 row_shl:14 row_mask:0xf bank_mask:0xf
	v_mov_b32_dpp v226, v216 row_shl:15 row_mask:0xf bank_mask:0xf
	v_mov_b32_dpp v227, v217 row_shl:15 row_mask:0xf bank_mask:0xf
	v_cndmask_b32_e64 v169, v216, 0, s[64:65]
	v_rcp_f32_e32 v78, v78
	v_sqrt_f32_e32 v172, v174
	v_mul_f32_e32 v79, 0xbfb8aa3b, v79
	v_exp_f32_e32 v77, v77
	v_lshlrev_b32_e32 v170, 16, v171
	v_and_b32_e32 v171, 0xffff0000, v171
	v_exp_f32_e32 v79, v79
	v_pk_fma_f32 v[162:163], v[42:43], v[170:171], v[162:163]
	v_cndmask_b32_e64 v171, v217, 0, s[64:65]
	v_add_f32_e32 v76, v32, v76
	v_lshlrev_b32_e32 v168, 16, v169
	v_and_b32_e32 v169, 0xffff0000, v169
	v_lshlrev_b32_e32 v170, 16, v171
	v_and_b32_e32 v171, 0xffff0000, v171
	v_mul_f32_e32 v76, 0xbfb8aa3b, v76
	v_pk_fma_f32 v[152:153], v[36:37], v[168:169], v[152:153]
	v_pk_fma_f32 v[168:169], v[38:39], v[170:171], v[162:163]
	v_mul_f32_e32 v78, v78, v172
	v_add_f32_e32 v77, 1.0, v77
	v_exp_f32_e32 v76, v76
	v_mul_f32_e32 v171, v168, v78
	v_add_f32_e32 v78, 1.0, v79
	v_rcp_f32_e32 v77, v77
	v_sqrt_f32_e32 v79, v147
	v_add_f32_e32 v76, 1.0, v76
	v_rcp_f32_e32 v76, v76
	v_rcp_f32_e32 v78, v78
	v_mul_f32_e32 v77, v77, v79
	v_sqrt_f32_e32 v79, v144
	v_mul_f32_e32 v80, 0x3fb8aa3b, v80
	v_exp_f32_e32 v80, v80
	v_mul_f32_e32 v144, v153, v77
	v_mul_f32_e32 v76, v76, v79
	v_sqrt_f32_e32 v79, v83
	v_mul_f32_e32 v168, v152, v76
	v_mul_f32_e32 v76, 0x3fb8aa3b, v81
	v_exp_f32_e32 v76, v76
	v_mul_f32_e32 v78, v78, v79
	v_mul_f32_e32 v172, v169, v78
	v_mov_b32_e32 v78, 1.0
	v_mov_b32_e32 v79, v145
	v_mul_f32_e32 v77, 0x3fb8aa3b, v82
	v_mov_b32_dpp v78, v80 row_shr:1 row_mask:0xf bank_mask:0xf
	v_mov_b32_dpp v79, v168 row_shr:1 row_mask:0xf bank_mask:0xf
	v_exp_f32_e32 v77, v77
	v_fmac_f32_e32 v168, v80, v79
	v_mul_f32_e32 v78, v80, v78
	v_mov_b32_e32 v80, v145
	v_mul_f32_e32 v147, 0x3fb8aa3b, v175
	v_exp_f32_e32 v147, v147
	v_mov_b32_dpp v80, v144 row_shr:1 row_mask:0xf bank_mask:0xf
	v_mov_b32_e32 v79, 1.0
	v_fmac_f32_e32 v144, v76, v80
	v_mov_b32_e32 v80, v145
	v_mov_b32_dpp v79, v76 row_shr:1 row_mask:0xf bank_mask:0xf
	v_mul_f32_e32 v76, v76, v79
	v_mov_b32_dpp v80, v171 row_shr:1 row_mask:0xf bank_mask:0xf
	v_mov_b32_e32 v79, 1.0
	v_fmac_f32_e32 v171, v77, v80
	v_mov_b32_e32 v80, v145
	v_mov_b32_dpp v79, v77 row_shr:1 row_mask:0xf bank_mask:0xf
	v_mul_f32_e32 v77, v77, v79
	v_mov_b32_dpp v80, v172 row_shr:1 row_mask:0xf bank_mask:0xf
	v_mov_b32_e32 v79, 1.0
	v_fmac_f32_e32 v172, v147, v80
	v_mov_b32_e32 v80, 1.0
	v_mov_b32_e32 v81, v145
	v_mov_b32_dpp v79, v147 row_shr:1 row_mask:0xf bank_mask:0xf
	v_mov_b32_dpp v80, v78 row_shr:2 row_mask:0xf bank_mask:0xf
	v_mov_b32_dpp v81, v168 row_shr:2 row_mask:0xf bank_mask:0xf
	v_mul_f32_e32 v79, v147, v79
	v_fmac_f32_e32 v168, v78, v81
	v_mul_f32_e32 v147, v78, v80
	v_mov_b32_e32 v78, 1.0
	v_mov_b32_e32 v80, v145
	s_waitcnt lgkmcnt(4)
	v_pk_fma_f32 v[162:163], v[86:87], 0, v[84:85] op_sel_hi:[1,0,1]
	v_mov_b32_dpp v78, v76 row_shr:2 row_mask:0xf bank_mask:0xf
	v_mov_b32_dpp v80, v144 row_shr:2 row_mask:0xf bank_mask:0xf
	v_fmac_f32_e32 v144, v76, v80
	v_mul_f32_e32 v169, v76, v78
	v_mov_b32_e32 v76, 1.0
	v_mov_b32_e32 v78, v145
	s_nop 0
	s_nop 0
	s_waitcnt vmcnt(8)
	v_lshlrev_b32_e32 v84, 16, v220
	v_mov_b32_dpp v76, v77 row_shr:2 row_mask:0xf bank_mask:0xf
	v_mul_f32_e32 v170, v77, v76
	v_mov_b32_e32 v76, 1.0
	v_mov_b32_dpp v78, v171 row_shr:2 row_mask:0xf bank_mask:0xf
	v_fmac_f32_e32 v171, v77, v78
	v_mov_b32_dpp v76, v79 row_shr:2 row_mask:0xf bank_mask:0xf
	v_mul_f32_e32 v173, v79, v76
	v_mov_b32_e32 v76, v145
	v_mov_b32_e32 v77, v145
	v_mul_f32_e32 v84, 0xbfb8aa3b, v84
	v_mov_b32_dpp v76, v168 row_shr:4 row_mask:0xf bank_mask:0xf
	v_fmac_f32_e32 v168, v147, v76
	v_mov_b32_e32 v76, v145
	v_mov_b32_dpp v77, v172 row_shr:2 row_mask:0xf bank_mask:0xf
	v_fmac_f32_e32 v172, v79, v77
	v_mov_b32_dpp v76, v144 row_shr:4 row_mask:0xf bank_mask:0xf
	v_fmac_f32_e32 v144, v169, v76
	v_mov_b32_e32 v76, v145
	v_mov_b32_e32 v77, 1.0
	v_exp_f32_e32 v153, v84
	v_mov_b32_dpp v76, v171 row_shr:4 row_mask:0xf bank_mask:0xf
	v_fmac_f32_e32 v171, v170, v76
	v_mov_b32_e32 v76, v145
	v_mov_b32_dpp v77, v147 row_shr:4 row_mask:0xf bank_mask:0xf
	v_mov_b32_e32 v152, v145
	v_mov_b32_dpp v76, v172 row_shr:4 row_mask:0xf bank_mask:0xf
	v_fmac_f32_e32 v172, v173, v76
	v_lshlrev_b32_e32 v76, 16, v218
	v_pk_mul_f32 v[84:85], v[146:147], v[76:77]
	v_mul_f32_e32 v77, 0x3d372713, v76
	v_mul_f32_e32 v77, v77, v76
	v_fmac_f32_e32 v76, v77, v76
	v_mul_f32_e32 v76, 0x3f4c422a, v76
	v_add_f32_e32 v76, v76, v76
	v_mul_f32_e32 v76, 0x3fb8aa3b, v76
	v_exp_f32_e32 v77, v76
	v_add_f32_e32 v76, 1.0, v153
	v_rcp_f32_e32 v76, v76
	v_mov_b32_dpp v152, v168 row_shr:8 row_mask:0xf bank_mask:0xf
	v_add_f32_e32 v77, 1.0, v77
	v_rcp_f32_e32 v77, v77
	v_mov_b32_e32 v153, 1.0
	v_fmac_f32_e32 v168, v85, v152
	v_mov_b32_e32 v79, 1.0
	v_fma_f32 v77, v77, -2.0, 1.0
	v_mov_b32_dpp v153, v85 row_shr:8 row_mask:0xf bank_mask:0xf
	v_add_f32_e32 v152, 1.0, v77
	v_pk_mul_f32 v[84:85], v[84:85], v[152:153]
	v_mov_b32_e32 v77, v162
	v_lshlrev_b32_e32 v80, 16, v219
	v_and_b32_e32 v82, 0xffff0000, v219
	v_and_b32_e32 v167, 0xffff0000, v220
	v_pk_mul_f32 v[76:77], v[76:77], v[84:85]
	v_mov_b32_dpp v79, v169 row_shr:4 row_mask:0xf bank_mask:0xf
	v_and_b32_e32 v78, 0xffff0000, v218
	v_add_f32_e32 v77, v77, v168
	v_mul_f32_e32 v84, 0xbfb8aa3b, v167
	v_mov_b32_e32 v147, v169
	ds_bpermute_b32 v164, v184, v85
	v_mul_f32_e32 v152, v76, v77
	v_mul_f32_e32 v77, v85, v86
	v_exp_f32_e32 v153, v84
	v_pk_mul_f32 v[84:85], v[146:147], v[78:79]
	v_mul_f32_e32 v79, 0x3d372713, v78
	v_mul_f32_e32 v79, v79, v78
	v_fmac_f32_e32 v78, v79, v78
	v_mul_f32_e32 v78, 0x3f4c422a, v78
	v_add_f32_e32 v78, v78, v78
	v_mul_f32_e32 v78, 0x3fb8aa3b, v78
	v_exp_f32_e32 v78, v78
	v_mul_f32_e32 v179, v76, v77
	v_add_f32_e32 v76, 1.0, v153
	v_rcp_f32_e32 v76, v76
	v_add_f32_e32 v77, 1.0, v78
	v_rcp_f32_e32 v77, v77
	v_mov_b32_e32 v79, 1.0
	v_mov_b32_e32 v174, v145
	v_mov_b32_e32 v81, 1.0
	v_fma_f32 v77, v77, -2.0, 1.0
	v_mov_b32_dpp v79, v85 row_shr:8 row_mask:0xf bank_mask:0xf
	v_add_f32_e32 v78, 1.0, v77
	v_mov_b32_dpp v174, v144 row_shr:8 row_mask:0xf bank_mask:0xf
	v_pk_mul_f32 v[78:79], v[84:85], v[78:79]
	v_mov_b32_e32 v77, v163
	v_lshlrev_b32_e32 v177, 16, v221
	v_fmac_f32_e32 v144, v85, v174
	v_pk_mul_f32 v[76:77], v[76:77], v[78:79]
	v_mov_b32_dpp v81, v170 row_shr:4 row_mask:0xf bank_mask:0xf
	v_add_f32_e32 v77, v77, v144
	v_mul_f32_e32 v78, 0xbfb8aa3b, v177
	v_mov_b32_e32 v147, v170
	v_and_b32_e32 v178, 0xffff0000, v221
	ds_bpermute_b32 v165, v184, v79
	v_mul_f32_e32 v84, v76, v77
	v_mul_f32_e32 v77, v79, v87
	v_exp_f32_e32 v85, v78
	v_pk_mul_f32 v[78:79], v[146:147], v[80:81]
	v_mul_f32_e32 v81, 0x3d372713, v80
	v_mul_f32_e32 v81, v81, v80
	v_fmac_f32_e32 v80, v81, v80
	v_mul_f32_e32 v80, 0x3f4c422a, v80
	v_add_f32_e32 v80, v80, v80
	v_mul_f32_e32 v80, 0x3fb8aa3b, v80
	v_exp_f32_e32 v80, v80
	ds_bpermute_b32 v167, v184, v144
	v_mul_f32_e32 v144, v76, v77
	v_add_f32_e32 v76, 1.0, v85
	v_add_f32_e32 v77, 1.0, v80
	v_rcp_f32_e32 v77, v77
	v_rcp_f32_e32 v76, v76
	v_mov_b32_e32 v175, v145
	v_mov_b32_e32 v81, 1.0
	v_fma_f32 v77, v77, -2.0, 1.0
	s_waitcnt lgkmcnt(3)
	v_pk_fma_f32 v[142:143], v[140:141], 0, v[142:143] op_sel_hi:[1,0,1]
	v_mov_b32_dpp v175, v171 row_shr:8 row_mask:0xf bank_mask:0xf
	v_mov_b32_dpp v81, v79 row_shr:8 row_mask:0xf bank_mask:0xf
	v_add_f32_e32 v80, 1.0, v77
	v_fmac_f32_e32 v171, v79, v175
	v_pk_mul_f32 v[78:79], v[78:79], v[80:81]
	v_mov_b32_e32 v77, v142
	v_mov_b32_e32 v83, 1.0
	v_pk_mul_f32 v[76:77], v[76:77], v[78:79]
	v_mul_f32_e32 v81, 0x3d372713, v82
	v_mov_b32_dpp v83, v173 row_shr:4 row_mask:0xf bank_mask:0xf
	v_add_f32_e32 v77, v77, v171
	v_mul_f32_e32 v78, 0xbfb8aa3b, v178
	v_mov_b32_e32 v147, v173
	v_mul_f32_e32 v81, v81, v82
	ds_bpermute_b32 v166, v184, v168
	ds_bpermute_b32 v168, v184, v79
	v_mul_f32_e32 v85, v76, v77
	v_mul_f32_e32 v77, v79, v140
	v_exp_f32_e32 v80, v78
	v_pk_mul_f32 v[78:79], v[146:147], v[82:83]
	v_fmac_f32_e32 v82, v81, v82
	v_mul_f32_e32 v81, 0x3f4c422a, v82
	v_add_f32_e32 v81, v81, v81
	v_mul_f32_e32 v81, 0x3fb8aa3b, v81
	v_exp_f32_e32 v81, v81
	v_mul_f32_e32 v82, v76, v77
	v_add_f32_e32 v76, 1.0, v80
	v_rcp_f32_e32 v76, v76
	v_add_f32_e32 v77, 1.0, v81
	v_rcp_f32_e32 v77, v77
	v_mov_b32_e32 v176, v145
	v_mov_b32_e32 v81, 1.0
	ds_bpermute_b32 v170, v184, v171
	v_fma_f32 v77, v77, -2.0, 1.0
	v_mov_b32_dpp v176, v172 row_shr:8 row_mask:0xf bank_mask:0xf
	v_mov_b32_dpp v81, v79 row_shr:8 row_mask:0xf bank_mask:0xf
	v_add_f32_e32 v80, 1.0, v77
	v_fmac_f32_e32 v172, v79, v176
	v_pk_mul_f32 v[78:79], v[78:79], v[80:81]
	v_mov_b32_e32 v77, v143
	v_pk_mul_f32 v[76:77], v[76:77], v[78:79]
	v_mul_f32_e32 v78, v79, v141
	v_add_f32_e32 v77, v77, v172
	v_mul_f32_e32 v77, v76, v77
	ds_bpermute_b32 v169, v184, v79
	ds_bpermute_b32 v171, v184, v172
	v_mul_f32_e32 v80, v76, v78
	v_cvt_pk_bf16_f32 v76, v152, v84
	v_cvt_pk_bf16_f32 v77, v85, v77
	v_lshl_add_u64 v[84:85], s[74:75], 0, v[132:133]
	s_mov_b32 s54, 0x25d49000
	v_add_co_u32_e32 v78, vcc, s54, v84
	s_mov_b32 s54, 0x27d49000
	s_nop 0
	v_addc_co_u32_e32 v79, vcc, 0, v85, vcc
	global_store_dwordx2 v[78:79], v[76:77], off
	v_add_co_u32_e32 v78, vcc, s54, v84
	v_cvt_pk_bf16_f32 v76, v179, v144
	v_cvt_pk_bf16_f32 v77, v82, v80
	s_nop 1
	v_addc_co_u32_e32 v79, vcc, 0, v85, vcc
	global_store_dwordx2 v[78:79], v[76:77], off
	s_mov_b32 s54, 0x13118000
	v_add_co_u32_e32 v80, vcc, s54, v138
	s_mov_b32 s54, 0x1311c000
	s_nop 0
	v_addc_co_u32_e32 v81, vcc, 0, v139, vcc
	s_nop 0
	v_add_co_u32_e32 v80, vcc, s54, v138
	s_mov_b32 s54, 0x13120000
	s_nop 0
	v_addc_co_u32_e32 v81, vcc, 0, v139, vcc
	s_nop 0
	v_add_co_u32_e32 v80, vcc, s54, v138
	s_mov_b32 s54, 0x13125000
	s_nop 0
	v_addc_co_u32_e32 v81, vcc, 0, v139, vcc
	v_add_co_u32_e32 v152, vcc, s54, v138
	s_nop 0
	s_nop 0
	v_addc_co_u32_e32 v153, vcc, 0, v139, vcc
	s_nop 0
	s_nop 0
	v_add_co_u32_e32 v152, vcc, 0x13128000, v138
	v_mfma_f32_16x16x32_bf16 v[80:83], v[72:75], v[8:11], 0
	s_nop 0
	v_addc_co_u32_e32 v153, vcc, 0, v139, vcc
	s_nop 0
	v_mfma_f32_16x16x32_bf16 v[80:83], v[60:63], v[24:27], v[80:83]
	v_mfma_f32_16x16x32_bf16 v[76:79], v[68:71], v[8:11], 0
	v_mfma_f32_16x16x32_bf16 v[76:79], v[64:67], v[24:27], v[76:79]
	s_nop 5
	v_add_f32_e32 v80, v56, v80
	v_mul_f32_e32 v80, 0xbfb8aa3b, v80
	v_exp_f32_e32 v80, v80
	s_nop 0
	v_add_f32_e32 v80, 1.0, v80
	v_rcp_f32_e32 v80, v80
	s_nop 0
	v_mul_f32_e32 v80, 0xc1000000, v80
	v_mul_f32_e32 v144, v185, v80
	v_add_f32_e32 v147, v144, v144
	v_cmp_nlt_f32_e32 vcc, s93, v147
	s_and_saveexec_b64 s[54:55], vcc
	s_xor_b64 s[54:55], exec, s[54:55]
	v_mul_f32_e32 v80, 0x3fb8aa3b, v147
	v_exp_f32_e32 v80, v80
	s_nop 0
	v_sub_f32_e32 v80, 1.0, v80
	s_andn2_saveexec_b64 s[54:55], s[54:55]
	v_fma_f32 v80, v147, s94, 0.5
	v_fma_f32 v80, v147, v80, 1.0
	v_mul_f32_e64 v80, v80, -v147
	s_or_b64 exec, exec, s[54:55]
	v_add_f32_e32 v81, v57, v81
	v_mul_f32_e32 v81, 0xbfb8aa3b, v81
	v_exp_f32_e32 v81, v81
	s_nop 0
	v_add_f32_e32 v81, 1.0, v81
	v_rcp_f32_e32 v81, v81
	s_nop 0
	v_mul_f32_e32 v81, 0xc1000000, v81
	v_mul_f32_e32 v81, v186, v81
	v_add_f32_e32 v189, v81, v81
	v_cmp_nlt_f32_e32 vcc, s93, v189
	s_and_saveexec_b64 s[54:55], vcc
	s_xor_b64 s[54:55], exec, s[54:55]
	v_mul_f32_e32 v147, 0x3fb8aa3b, v189
	v_exp_f32_e32 v147, v147
	s_nop 0
	v_sub_f32_e32 v147, 1.0, v147
	s_andn2_saveexec_b64 s[54:55], s[54:55]
	v_fma_f32 v147, v189, s94, 0.5
	v_fma_f32 v147, v189, v147, 1.0
	v_mul_f32_e64 v147, v147, -v189
	s_or_b64 exec, exec, s[54:55]
	v_add_f32_e32 v82, v58, v82
	v_mul_f32_e32 v82, 0xbfb8aa3b, v82
	v_exp_f32_e32 v82, v82
	s_nop 0
	v_add_f32_e32 v82, 1.0, v82
	v_rcp_f32_e32 v82, v82
	s_nop 0
	v_mul_f32_e32 v82, 0xc1000000, v82
	v_mul_f32_e32 v82, v187, v82
	v_add_f32_e32 v189, v82, v82
	v_cmp_nlt_f32_e32 vcc, s93, v189
	s_and_saveexec_b64 s[54:55], vcc
	s_xor_b64 s[54:55], exec, s[54:55]
	v_mul_f32_e32 v152, 0x3fb8aa3b, v189
	v_exp_f32_e32 v152, v152
	s_nop 0
	v_sub_f32_e32 v190, 1.0, v152
	s_andn2_saveexec_b64 s[54:55], s[54:55]
	v_fma_f32 v152, v189, s94, 0.5
	v_fma_f32 v152, v189, v152, 1.0
	v_mul_f32_e64 v190, v152, -v189
	s_or_b64 exec, exec, s[54:55]
	v_add_f32_e32 v83, v59, v83
	v_mul_f32_e32 v83, 0xbfb8aa3b, v83
	v_exp_f32_e32 v83, v83
	s_nop 0
	v_add_f32_e32 v83, 1.0, v83
	v_rcp_f32_e32 v83, v83
	s_nop 0
	v_mul_f32_e32 v83, 0xc1000000, v83
	v_mul_f32_e32 v83, v188, v83
	v_add_f32_e32 v191, v83, v83
	v_cmp_nlt_f32_e32 vcc, s93, v191
	s_and_saveexec_b64 s[54:55], vcc
	s_xor_b64 s[54:55], exec, s[54:55]
	v_mul_f32_e32 v152, 0x3fb8aa3b, v191
	v_exp_f32_e32 v152, v152
	s_nop 0
	v_sub_f32_e32 v189, 1.0, v152
	s_andn2_saveexec_b64 s[54:55], s[54:55]
	v_fma_f32 v152, v191, s94, 0.5
	v_fma_f32 v152, v191, v152, 1.0
	v_mul_f32_e64 v189, v152, -v191
	s_or_b64 exec, exec, s[54:55]
	v_add_f32_e32 v78, v34, v78
	v_mul_f32_e32 v78, 0xbfb8aa3b, v78
	s_nop 0
	s_nop 0
	s_waitcnt vmcnt(9)
	v_mov_b32_dpp v222, v228 row_shr:3 row_mask:0xf bank_mask:0xf
	v_mov_b32_dpp v223, v229 row_shr:3 row_mask:0xf bank_mask:0xf
	v_mov_b32_dpp v224, v228 row_shr:2 row_mask:0xf bank_mask:0xf
	v_mov_b32_dpp v225, v229 row_shr:2 row_mask:0xf bank_mask:0xf
	v_mov_b32_dpp v226, v228 row_shr:1 row_mask:0xf bank_mask:0xf
	v_mov_b32_dpp v227, v229 row_shr:1 row_mask:0xf bank_mask:0xf
	v_cndmask_b32_e64 v181, v223, 0, s[42:43]
	v_cndmask_b32_e64 v153, v222, 0, s[42:43]
	v_exp_f32_e32 v78, v78
	v_lshlrev_b32_e32 v152, 16, v153
	v_and_b32_e32 v153, 0xffff0000, v153
	v_lshlrev_b32_e32 v180, 16, v181
	v_and_b32_e32 v181, 0xffff0000, v181
	s_nop 0
	s_nop 0
	v_cndmask_b32_e64 v191, v225, 0, s[44:45]
	v_cndmask_b32_e64 v177, v224, 0, s[44:45]
	v_pk_fma_f32 v[180:181], v[50:51], v[180:181], v[54:55]
	v_pk_fma_f32 v[152:153], v[48:49], v[152:153], v[52:53]
	v_lshlrev_b32_e32 v176, 16, v177
	v_and_b32_e32 v177, 0xffff0000, v177
	v_lshlrev_b32_e32 v192, 16, v191
	v_and_b32_e32 v193, 0xffff0000, v191
	v_pk_fma_f32 v[152:153], v[44:45], v[176:177], v[152:153]
	v_pk_fma_f32 v[176:177], v[46:47], v[192:193], v[180:181]
	s_nop 0
	s_nop 0
	v_cndmask_b32_e64 v181, v227, 0, s[46:47]
	v_cndmask_b32_e64 v179, v226, 0, s[46:47]
	v_lshlrev_b32_e32 v178, 16, v179
	v_and_b32_e32 v179, 0xffff0000, v179
	v_add_f32_e32 v78, 1.0, v78
	v_add_f32_e32 v79, v35, v79
	v_add_f32_e32 v77, v33, v77
	v_pk_fma_f32 v[152:153], v[40:41], v[178:179], v[152:153]
	s_nop 0
	s_nop 0
	v_mov_b32_dpp v234, v228 row_shl:13 row_mask:0xf bank_mask:0xf
	v_mov_b32_dpp v235, v229 row_shl:13 row_mask:0xf bank_mask:0xf
	v_mov_b32_dpp v236, v228 row_shl:14 row_mask:0xf bank_mask:0xf
	v_mov_b32_dpp v237, v229 row_shl:14 row_mask:0xf bank_mask:0xf
	v_mov_b32_dpp v238, v228 row_shl:15 row_mask:0xf bank_mask:0xf
	v_mov_b32_dpp v239, v229 row_shl:15 row_mask:0xf bank_mask:0xf
	v_cndmask_b32_e64 v179, v228, 0, s[64:65]
	v_rcp_f32_e32 v78, v78
	v_sqrt_f32_e32 v182, v190
	v_mul_f32_e32 v79, 0xbfb8aa3b, v79
	v_mul_f32_e32 v77, 0xbfb8aa3b, v77
	v_lshlrev_b32_e32 v180, 16, v181
	v_and_b32_e32 v181, 0xffff0000, v181
	v_exp_f32_e32 v79, v79
	v_exp_f32_e32 v77, v77
	v_pk_fma_f32 v[176:177], v[42:43], v[180:181], v[176:177]
	v_cndmask_b32_e64 v181, v229, 0, s[64:65]
	v_lshlrev_b32_e32 v180, 16, v181
	v_and_b32_e32 v181, 0xffff0000, v181
	v_add_f32_e32 v76, v32, v76
	v_pk_fma_f32 v[176:177], v[38:39], v[180:181], v[176:177]
	v_mul_f32_e32 v78, v78, v182
	v_mul_f32_e32 v76, 0xbfb8aa3b, v76
	v_lshlrev_b32_e32 v178, 16, v179
	v_and_b32_e32 v179, 0xffff0000, v179
	v_mul_f32_e32 v176, v176, v78
	v_add_f32_e32 v78, 1.0, v79
	v_add_f32_e32 v77, 1.0, v77
	v_exp_f32_e32 v76, v76
	v_pk_fma_f32 v[152:153], v[36:37], v[178:179], v[152:153]
	v_rcp_f32_e32 v178, v78
	v_rcp_f32_e32 v77, v77
	v_sqrt_f32_e32 v78, v147
	v_add_f32_e32 v76, 1.0, v76
	v_rcp_f32_e32 v76, v76
	v_mul_f32_e32 v79, 0x3fb8aa3b, v83
	v_mul_f32_e32 v77, v77, v78
	v_sqrt_f32_e32 v78, v80
	v_mul_f32_e32 v179, v153, v77
	v_mul_f32_e32 v77, 0x3fb8aa3b, v82
	s_waitcnt lgkmcnt(6)
	v_pk_mul_f32 v[82:83], v[86:87], v[164:165]
	v_sqrt_f32_e32 v86, v189
	v_mul_f32_e32 v87, 0x3fb8aa3b, v144
	v_mul_f32_e32 v76, v76, v78
	v_exp_f32_e32 v87, v87
	v_exp_f32_e32 v147, v79
	v_exp_f32_e32 v153, v77
	v_mul_f32_e32 v180, v152, v76
	v_mul_f32_e32 v76, 0x3fb8aa3b, v81
	v_exp_f32_e32 v152, v76
	v_mul_f32_e32 v86, v178, v86
	s_waitcnt lgkmcnt(1)
	v_pk_mul_f32 v[78:79], v[140:141], v[168:169]
	s_waitcnt lgkmcnt(0)
	v_pk_fma_f32 v[76:77], v[142:143], v[168:169], v[170:171]
	v_mul_f32_e32 v144, v177, v86
	v_mov_b32_e32 v86, 1.0
	v_mov_b32_e32 v140, v145
	v_mov_b32_e32 v141, v145
	v_mov_b32_e32 v142, v145
	v_mov_b32_dpp v86, v87 row_shr:1 row_mask:0xf bank_mask:0xf
	v_mov_b32_dpp v140, v180 row_shr:1 row_mask:0xf bank_mask:0xf
	v_mov_b32_dpp v141, v176 row_shr:1 row_mask:0xf bank_mask:0xf
	v_mov_b32_dpp v142, v144 row_shr:1 row_mask:0xf bank_mask:0xf
	v_fmac_f32_e32 v180, v87, v140
	v_mul_f32_e32 v86, v87, v86
	v_mov_b32_e32 v87, 1.0
	v_mov_b32_e32 v140, v145
	v_fmac_f32_e32 v176, v153, v141
	v_mov_b32_e32 v141, 1.0
	v_fmac_f32_e32 v144, v147, v142
	v_mov_b32_e32 v142, 1.0
	v_mov_b32_e32 v143, v145
	v_mov_b32_dpp v87, v152 row_shr:1 row_mask:0xf bank_mask:0xf
	v_mov_b32_dpp v140, v179 row_shr:1 row_mask:0xf bank_mask:0xf
	v_mov_b32_dpp v141, v147 row_shr:1 row_mask:0xf bank_mask:0xf
	v_mov_b32_dpp v142, v86 row_shr:2 row_mask:0xf bank_mask:0xf
	v_mov_b32_dpp v143, v180 row_shr:2 row_mask:0xf bank_mask:0xf
	v_fmac_f32_e32 v179, v152, v140
	v_mul_f32_e32 v87, v152, v87
	v_mov_b32_e32 v140, 1.0
	v_mul_f32_e32 v141, v147, v141
	v_fmac_f32_e32 v180, v86, v143
	v_mul_f32_e32 v147, v86, v142
	v_mov_b32_e32 v86, 1.0
	v_mov_b32_dpp v140, v153 row_shr:1 row_mask:0xf bank_mask:0xf
	v_mul_f32_e32 v140, v153, v140
	v_mov_b32_dpp v86, v87 row_shr:2 row_mask:0xf bank_mask:0xf
	v_mul_f32_e32 v168, v87, v86
	v_mov_b32_e32 v86, 1.0
	v_mov_b32_e32 v142, v145
	v_pk_fma_f32 v[80:81], v[162:163], v[164:165], v[166:167]
	v_mov_b32_dpp v86, v140 row_shr:2 row_mask:0xf bank_mask:0xf
	v_mul_f32_e32 v169, v140, v86
	v_mov_b32_e32 v86, 1.0
	v_mov_b32_dpp v142, v179 row_shr:2 row_mask:0xf bank_mask:0xf
	v_fmac_f32_e32 v179, v87, v142
	v_mov_b32_dpp v86, v141 row_shr:2 row_mask:0xf bank_mask:0xf
	v_mul_f32_e32 v170, v141, v86
	v_mov_b32_e32 v86, v145
	v_mov_b32_e32 v87, v145
	v_mov_b32_e32 v163, v145
	v_mov_b32_dpp v86, v180 row_shr:4 row_mask:0xf bank_mask:0xf
	v_fmac_f32_e32 v180, v147, v86
	v_mov_b32_e32 v86, v145
	v_mov_b32_dpp v87, v176 row_shr:2 row_mask:0xf bank_mask:0xf
	v_fmac_f32_e32 v176, v140, v87
	v_mov_b32_dpp v86, v179 row_shr:4 row_mask:0xf bank_mask:0xf
	v_mov_b32_e32 v87, v145
	v_fmac_f32_e32 v179, v168, v86
	v_mov_b32_e32 v86, v145
	v_mov_b32_dpp v87, v144 row_shr:2 row_mask:0xf bank_mask:0xf
	v_fmac_f32_e32 v144, v141, v87
	v_mov_b32_dpp v86, v176 row_shr:4 row_mask:0xf bank_mask:0xf
	v_fmac_f32_e32 v176, v169, v86
	v_mov_b32_e32 v86, v145
	v_mov_b32_e32 v87, 1.0
	s_nop 0
	s_nop 0
	s_waitcnt vmcnt(7)
	v_lshlrev_b32_e32 v140, 16, v232
	v_mov_b32_dpp v86, v144 row_shr:4 row_mask:0xf bank_mask:0xf
	v_mov_b32_dpp v87, v147 row_shr:4 row_mask:0xf bank_mask:0xf
	v_fmac_f32_e32 v144, v170, v86
	v_lshlrev_b32_e32 v86, 16, v230
	v_mul_f32_e32 v140, 0xbfb8aa3b, v140
	v_exp_f32_e32 v162, v140
	v_pk_mul_f32 v[140:141], v[146:147], v[86:87]
	v_mul_f32_e32 v87, 0x3d372713, v86
	v_mul_f32_e32 v87, v87, v86
	v_fmac_f32_e32 v86, v87, v86
	v_mul_f32_e32 v86, 0x3f4c422a, v86
	v_add_f32_e32 v86, v86, v86
	v_mul_f32_e32 v86, 0x3fb8aa3b, v86
	v_exp_f32_e32 v86, v86
	v_add_f32_e32 v87, 1.0, v162
	v_rcp_f32_e32 v162, v87
	v_mov_b32_e32 v87, 1.0
	v_add_f32_e32 v86, 1.0, v86
	v_rcp_f32_e32 v86, v86
	v_mov_b32_e32 v143, 1.0
	v_mov_b32_dpp v163, v180 row_shr:8 row_mask:0xf bank_mask:0xf
	v_mov_b32_dpp v87, v141 row_shr:8 row_mask:0xf bank_mask:0xf
	v_fma_f32 v86, v86, -2.0, 1.0
	v_add_f32_e32 v86, 1.0, v86
	v_mov_b32_dpp v143, v168 row_shr:4 row_mask:0xf bank_mask:0xf
	v_and_b32_e32 v142, 0xffff0000, v230
	v_fmac_f32_e32 v180, v141, v163
	v_pk_mul_f32 v[166:167], v[140:141], v[86:87]
	v_mov_b32_e32 v163, v80
	v_mov_b32_e32 v147, v168
	ds_bpermute_b32 v86, v184, v167
	v_mul_f32_e32 v87, v82, v167
	v_pk_mul_f32 v[162:163], v[162:163], v[166:167]
	v_pk_mul_f32 v[166:167], v[146:147], v[142:143]
	v_mul_f32_e32 v143, 0x3d372713, v142
	v_mul_f32_e32 v143, v143, v142
	v_fmac_f32_e32 v142, v143, v142
	v_and_b32_e32 v172, 0xffff0000, v232
	v_add_f32_e32 v141, v163, v180
	v_mul_f32_e32 v142, 0x3f4c422a, v142
	v_lshlrev_b32_e32 v152, 16, v231
	v_and_b32_e32 v164, 0xffff0000, v231
	v_mul_f32_e32 v175, v162, v141
	v_mul_f32_e32 v141, 0xbfb8aa3b, v172
	v_add_f32_e32 v142, v142, v142
	v_exp_f32_e32 v141, v141
	v_mul_f32_e32 v142, 0x3fb8aa3b, v142
	v_exp_f32_e32 v143, v142
	v_mul_f32_e32 v168, v162, v87
	v_add_f32_e32 v87, 1.0, v141
	v_rcp_f32_e32 v142, v87
	v_add_f32_e32 v87, 1.0, v143
	v_rcp_f32_e32 v87, v87
	v_mov_b32_e32 v163, 1.0
	v_mov_b32_e32 v153, 1.0
	v_mov_b32_e32 v143, v81
	v_fma_f32 v87, v87, -2.0, 1.0
	v_mov_b32_dpp v163, v167 row_shr:8 row_mask:0xf bank_mask:0xf
	v_add_f32_e32 v162, 1.0, v87
	v_mov_b32_dpp v153, v169 row_shr:4 row_mask:0xf bank_mask:0xf
	v_pk_mul_f32 v[162:163], v[166:167], v[162:163]
	v_mov_b32_e32 v147, v169
	v_mov_b32_e32 v171, v145
	ds_bpermute_b32 v87, v184, v163
	v_mul_f32_e32 v166, v83, v163
	v_pk_mul_f32 v[142:143], v[142:143], v[162:163]
	v_pk_mul_f32 v[162:163], v[146:147], v[152:153]
	v_mul_f32_e32 v147, 0x3d372713, v152
	v_mov_b32_dpp v171, v179 row_shr:8 row_mask:0xf bank_mask:0xf
	v_mul_f32_e32 v147, v147, v152
	v_fmac_f32_e32 v179, v167, v171
	v_fmac_f32_e32 v152, v147, v152
	v_lshlrev_b32_e32 v174, 16, v233
	v_add_f32_e32 v143, v143, v179
	v_mul_f32_e32 v147, 0x3f4c422a, v152
	v_mul_f32_e32 v171, v142, v143
	v_mul_f32_e32 v143, 0xbfb8aa3b, v174
	v_add_f32_e32 v147, v147, v147
	v_exp_f32_e32 v143, v143
	v_mul_f32_e32 v147, 0x3fb8aa3b, v147
	v_exp_f32_e32 v147, v147
	v_mul_f32_e32 v169, v142, v166
	v_add_f32_e32 v142, 1.0, v143
	v_rcp_f32_e32 v152, v142
	v_add_f32_e32 v142, 1.0, v147
	v_rcp_f32_e32 v142, v142
	v_mov_b32_e32 v143, 1.0
	v_mov_b32_e32 v177, v145
	v_mov_b32_e32 v153, v76
	v_fma_f32 v142, v142, -2.0, 1.0
	v_mov_b32_dpp v143, v163 row_shr:8 row_mask:0xf bank_mask:0xf
	v_add_f32_e32 v142, 1.0, v142
	v_mov_b32_dpp v177, v176 row_shr:8 row_mask:0xf bank_mask:0xf
	v_pk_mul_f32 v[166:167], v[162:163], v[142:143]
	v_fmac_f32_e32 v176, v163, v177
	v_pk_mul_f32 v[152:153], v[152:153], v[166:167]
	v_and_b32_e32 v173, 0xffff0000, v233
	v_add_f32_e32 v147, v153, v176
	v_mov_b32_e32 v165, 1.0
	v_mul_f32_e32 v172, v152, v147
	v_mul_f32_e32 v147, 0xbfb8aa3b, v173
	v_mov_b32_dpp v165, v170 row_shr:4 row_mask:0xf bank_mask:0xf
	v_exp_f32_e32 v153, v147
	v_mov_b32_e32 v147, v170
	ds_bpermute_b32 v142, v184, v167
	v_mul_f32_e32 v143, v78, v167
	v_pk_mul_f32 v[166:167], v[146:147], v[164:165]
	v_mul_f32_e32 v147, 0x3d372713, v164
	v_mul_f32_e32 v147, v147, v164
	v_fmac_f32_e32 v164, v147, v164
	v_mul_f32_e32 v147, 0x3f4c422a, v164
	v_add_f32_e32 v147, v147, v147
	v_mul_f32_e32 v147, 0x3fb8aa3b, v147
	v_exp_f32_e32 v147, v147
	v_mul_f32_e32 v170, v152, v143
	v_add_f32_e32 v143, 1.0, v153
	v_rcp_f32_e32 v152, v143
	v_add_f32_e32 v143, 1.0, v147
	v_rcp_f32_e32 v143, v143
	v_mov_b32_e32 v178, v145
	v_mov_b32_e32 v165, 1.0
	ds_bpermute_b32 v140, v184, v180
	v_fma_f32 v143, v143, -2.0, 1.0
	v_mov_b32_dpp v178, v144 row_shr:8 row_mask:0xf bank_mask:0xf
	v_mov_b32_dpp v165, v167 row_shr:8 row_mask:0xf bank_mask:0xf
	v_add_f32_e32 v164, 1.0, v143
	v_fmac_f32_e32 v144, v167, v178
	v_pk_mul_f32 v[164:165], v[166:167], v[164:165]
	ds_bpermute_b32 v141, v184, v179
	ds_bpermute_b32 v162, v184, v176
	ds_bpermute_b32 v143, v184, v165
	ds_bpermute_b32 v163, v184, v144
	v_mov_b32_e32 v153, v77
	s_mov_b32 s54, 0x25d51000
	v_pk_mul_f32 v[152:153], v[152:153], v[164:165]
	v_add_co_u32_e32 v164, vcc, s54, v84
	v_mul_f32_e32 v147, v79, v165
	v_add_f32_e32 v144, v153, v144
	v_addc_co_u32_e32 v165, vcc, 0, v85, vcc
	s_mov_b32 s54, 0x27d51000
	v_mul_f32_e32 v144, v152, v144
	v_mul_f32_e32 v147, v152, v147
	v_cvt_pk_bf16_f32 v152, v175, v171
	v_cvt_pk_bf16_f32 v153, v172, v144
	global_store_dwordx2 v[164:165], v[152:153], off
	v_add_co_u32_e32 v164, vcc, s54, v84
	v_cvt_pk_bf16_f32 v152, v168, v169
	v_cvt_pk_bf16_f32 v153, v170, v147
	s_nop 1
	v_addc_co_u32_e32 v165, vcc, 0, v85, vcc
	global_store_dwordx2 v[164:165], v[152:153], off
	s_mov_b32 s54, 0x1315a000
	v_add_co_u32_e32 v152, vcc, s54, v138
	s_mov_b32 s54, 0x1315e000
	s_nop 0
	v_addc_co_u32_e32 v153, vcc, 0, v139, vcc
	v_add_co_u32_e32 v164, vcc, s54, v138
	s_mov_b32 s54, 0x13162000
	s_nop 0
	v_addc_co_u32_e32 v165, vcc, 0, v139, vcc
	v_add_co_u32_e32 v166, vcc, s54, v138
	s_mov_b32 s54, 0x13167000
	s_nop 0
	v_addc_co_u32_e32 v167, vcc, 0, v139, vcc
	v_add_co_u32_e32 v174, vcc, s54, v138
	v_mfma_f32_16x16x32_bf16 v[72:75], v[72:75], v[12:15], 0
	s_nop 0
	v_addc_co_u32_e32 v175, vcc, 0, v139, vcc
	s_nop 0
	s_nop 0
	s_nop 0
	s_nop 0
	s_nop 0
	v_add_co_u32_e32 v138, vcc, 0x1316a000, v138
	v_mfma_f32_16x16x32_bf16 v[72:75], v[60:63], v[28:31], v[72:75]
	s_nop 0
	v_addc_co_u32_e32 v139, vcc, 0, v139, vcc
	s_nop 0
	s_nop 0
	s_nop 0
	s_nop 2
	v_add_f32_e32 v56, v56, v72
	v_mul_f32_e32 v56, 0xbfb8aa3b, v56
	v_exp_f32_e32 v56, v56
	v_mfma_f32_16x16x32_bf16 v[60:63], v[68:71], v[12:15], 0
	v_add_f32_e32 v56, 1.0, v56
	v_rcp_f32_e32 v56, v56
	v_mfma_f32_16x16x32_bf16 v[60:63], v[64:67], v[28:31], v[60:63]
	v_mul_f32_e32 v56, 0xc1000000, v56
	v_mul_f32_e32 v56, v185, v56
	v_add_f32_e32 v65, v56, v56
	v_cmp_nlt_f32_e32 vcc, s93, v65
	s_and_saveexec_b64 s[54:55], vcc
	s_xor_b64 s[54:55], exec, s[54:55]
	v_mul_f32_e32 v64, 0x3fb8aa3b, v65
	v_exp_f32_e32 v64, v64
	s_nop 0
	v_sub_f32_e32 v64, 1.0, v64
	s_andn2_saveexec_b64 s[54:55], s[54:55]
	v_fma_f32 v64, v65, s94, 0.5
	v_fma_f32 v64, v65, v64, 1.0
	v_mul_f32_e64 v64, v64, -v65
	s_or_b64 exec, exec, s[54:55]
	v_add_f32_e32 v57, v57, v73
	v_mul_f32_e32 v57, 0xbfb8aa3b, v57
	v_exp_f32_e32 v57, v57
	s_nop 0
	v_add_f32_e32 v57, 1.0, v57
	v_rcp_f32_e32 v57, v57
	s_nop 0
	v_mul_f32_e32 v57, 0xc1000000, v57
	v_mul_f32_e32 v57, v186, v57
	v_add_f32_e32 v66, v57, v57
	v_cmp_nlt_f32_e32 vcc, s93, v66
	s_and_saveexec_b64 s[54:55], vcc
	s_xor_b64 s[54:55], exec, s[54:55]
	v_mul_f32_e32 v65, 0x3fb8aa3b, v66
	v_exp_f32_e32 v65, v65
	s_nop 0
	v_sub_f32_e32 v65, 1.0, v65
	s_andn2_saveexec_b64 s[54:55], s[54:55]
	v_fma_f32 v65, v66, s94, 0.5
	v_fma_f32 v65, v66, v65, 1.0
	v_mul_f32_e64 v65, v65, -v66
	s_or_b64 exec, exec, s[54:55]
	v_add_f32_e32 v58, v58, v74
	v_mul_f32_e32 v58, 0xbfb8aa3b, v58
	v_exp_f32_e32 v58, v58
	s_nop 0
	v_add_f32_e32 v58, 1.0, v58
	v_rcp_f32_e32 v58, v58
	s_nop 0
	v_mul_f32_e32 v58, 0xc1000000, v58
	v_mul_f32_e32 v58, v187, v58
	v_add_f32_e32 v67, v58, v58
	v_cmp_nlt_f32_e32 vcc, s93, v67
	s_and_saveexec_b64 s[54:55], vcc
	s_xor_b64 s[54:55], exec, s[54:55]
	v_mul_f32_e32 v66, 0x3fb8aa3b, v67
	v_exp_f32_e32 v66, v66
	s_nop 0
	v_sub_f32_e32 v66, 1.0, v66
	s_andn2_saveexec_b64 s[54:55], s[54:55]
	v_fma_f32 v66, v67, s94, 0.5
	v_fma_f32 v66, v67, v66, 1.0
	v_mul_f32_e64 v66, v66, -v67
	s_or_b64 exec, exec, s[54:55]
	v_add_f32_e32 v59, v59, v75
	v_mul_f32_e32 v59, 0xbfb8aa3b, v59
	v_exp_f32_e32 v59, v59
	s_nop 0
	v_add_f32_e32 v59, 1.0, v59
	v_rcp_f32_e32 v59, v59
	s_nop 0
	v_mul_f32_e32 v59, 0xc1000000, v59
	v_mul_f32_e32 v67, v188, v59
	v_add_f32_e32 v68, v67, v67
	v_cmp_nlt_f32_e32 vcc, s93, v68
	s_and_saveexec_b64 s[54:55], vcc
	s_xor_b64 s[54:55], exec, s[54:55]
	v_mul_f32_e32 v59, 0x3fb8aa3b, v68
	v_exp_f32_e32 v59, v59
	s_nop 0
	v_sub_f32_e32 v59, 1.0, v59
	s_andn2_saveexec_b64 s[54:55], s[54:55]
	v_fma_f32 v59, v68, s94, 0.5
	v_fma_f32 v59, v68, v59, 1.0
	v_mul_f32_e64 v59, v59, -v68
	s_or_b64 exec, exec, s[54:55]
	v_add_f32_e32 v34, v34, v62
	s_nop 0
	s_nop 0
	s_waitcnt vmcnt(8)
	v_mov_b32_dpp v234, v242 row_shr:3 row_mask:0xf bank_mask:0xf
	v_mov_b32_dpp v235, v243 row_shr:3 row_mask:0xf bank_mask:0xf
	v_mov_b32_dpp v236, v242 row_shr:2 row_mask:0xf bank_mask:0xf
	v_mov_b32_dpp v237, v243 row_shr:2 row_mask:0xf bank_mask:0xf
	v_mov_b32_dpp v238, v242 row_shr:1 row_mask:0xf bank_mask:0xf
	v_mov_b32_dpp v239, v243 row_shr:1 row_mask:0xf bank_mask:0xf
	v_cndmask_b32_e64 v69, v234, 0, s[48:49]
	v_mul_f32_e32 v34, 0xbfb8aa3b, v34
	v_lshlrev_b32_e32 v68, 16, v69
	v_and_b32_e32 v69, 0xffff0000, v69
	v_exp_f32_e32 v34, v34
	v_cndmask_b32_e64 v71, v235, 0, s[48:49]
	v_pk_fma_f32 v[48:49], v[48:49], v[68:69], v[52:53]
	s_nop 0
	s_nop 0
	v_cndmask_b32_e64 v53, v236, 0, s[50:51]
	v_lshlrev_b32_e32 v70, 16, v71
	v_and_b32_e32 v71, 0xffff0000, v71
	v_lshlrev_b32_e32 v52, 16, v53
	v_and_b32_e32 v53, 0xffff0000, v53
	v_pk_fma_f32 v[50:51], v[50:51], v[70:71], v[54:55]
	v_cndmask_b32_e64 v55, v237, 0, s[50:51]
	v_pk_fma_f32 v[44:45], v[44:45], v[52:53], v[48:49]
	s_nop 0
	s_nop 0
	v_cndmask_b32_e64 v49, v238, 0, s[52:53]
	v_lshlrev_b32_e32 v54, 16, v55
	v_and_b32_e32 v55, 0xffff0000, v55
	v_lshlrev_b32_e32 v48, 16, v49
	v_and_b32_e32 v49, 0xffff0000, v49
	v_add_f32_e32 v34, 1.0, v34
	v_add_f32_e32 v35, v35, v63
	v_add_f32_e32 v33, v33, v61
	v_pk_fma_f32 v[46:47], v[46:47], v[54:55], v[50:51]
	v_cndmask_b32_e64 v51, v239, 0, s[52:53]
	v_pk_fma_f32 v[40:41], v[40:41], v[48:49], v[44:45]
	v_rcp_f32_e32 v34, v34
	v_sqrt_f32_e32 v48, v66
	v_mul_f32_e32 v35, 0xbfb8aa3b, v35
	v_mul_f32_e32 v33, 0xbfb8aa3b, v33
	v_lshlrev_b32_e32 v50, 16, v51
	v_and_b32_e32 v51, 0xffff0000, v51
	v_exp_f32_e32 v35, v35
	v_exp_f32_e32 v33, v33
	v_pk_fma_f32 v[42:43], v[42:43], v[50:51], v[46:47]
	s_nop 0
	s_nop 0
	v_cndmask_b32_e64 v47, v243, 0, s[64:65]
	v_cndmask_b32_e64 v45, v242, 0, s[64:65]
	v_lshlrev_b32_e32 v44, 16, v45
	v_and_b32_e32 v45, 0xffff0000, v45
	v_lshlrev_b32_e32 v46, 16, v47
	v_and_b32_e32 v47, 0xffff0000, v47
	v_add_f32_e32 v32, v32, v60
	v_pk_fma_f32 v[36:37], v[36:37], v[44:45], v[40:41]
	v_pk_fma_f32 v[40:41], v[38:39], v[46:47], v[42:43]
	v_mul_f32_e32 v34, v34, v48
	v_mul_f32_e32 v32, 0xbfb8aa3b, v32
	v_mul_f32_e32 v54, v40, v34
	v_add_f32_e32 v34, 1.0, v35
	v_add_f32_e32 v33, 1.0, v33
	v_exp_f32_e32 v32, v32
	v_rcp_f32_e32 v40, v34
	v_rcp_f32_e32 v33, v33
	v_sqrt_f32_e32 v34, v65
	v_add_f32_e32 v32, 1.0, v32
	v_rcp_f32_e32 v32, v32
	v_sqrt_f32_e32 v45, v59
	v_mul_f32_e32 v33, v33, v34
	v_sqrt_f32_e32 v34, v64
	v_mul_f32_e32 v46, 0x3fb8aa3b, v56
	v_mul_f32_e32 v55, v37, v33
	v_mul_f32_e32 v33, 0x3fb8aa3b, v58
	v_mul_f32_e32 v32, v32, v34
	v_mul_f32_e32 v58, v36, v32
	v_mul_f32_e32 v32, 0x3fb8aa3b, v57
	v_exp_f32_e32 v46, v46
	v_exp_f32_e32 v44, v32
	v_mul_f32_e32 v40, v40, v45
	v_mul_f32_e32 v56, v41, v40
	v_mov_b32_e32 v41, v145
	v_exp_f32_e32 v43, v33
	v_mul_f32_e32 v35, 0x3fb8aa3b, v67
	v_mov_b32_dpp v41, v58 row_shr:1 row_mask:0xf bank_mask:0xf
	v_fmac_f32_e32 v58, v46, v41
	v_mov_b32_e32 v41, 1.0
	v_mov_b32_e32 v45, v145
	v_exp_f32_e32 v42, v35
	v_mov_b32_dpp v41, v44 row_shr:1 row_mask:0xf bank_mask:0xf
	v_mov_b32_dpp v45, v55 row_shr:1 row_mask:0xf bank_mask:0xf
	v_fmac_f32_e32 v55, v44, v45
	v_mul_f32_e32 v41, v44, v41
	v_mov_b32_e32 v44, 1.0
	v_mov_b32_e32 v45, v145
	v_mov_b32_e32 v40, 1.0
	v_mov_b32_dpp v44, v43 row_shr:1 row_mask:0xf bank_mask:0xf
	v_mov_b32_dpp v45, v54 row_shr:1 row_mask:0xf bank_mask:0xf
	v_fmac_f32_e32 v54, v43, v45
	v_mul_f32_e32 v43, v43, v44
	v_mov_b32_e32 v44, 1.0
	v_mov_b32_e32 v45, v145
	v_mov_b32_dpp v40, v46 row_shr:1 row_mask:0xf bank_mask:0xf
	v_mov_b32_dpp v44, v42 row_shr:1 row_mask:0xf bank_mask:0xf
	v_mov_b32_dpp v45, v56 row_shr:1 row_mask:0xf bank_mask:0xf
	v_mul_f32_e32 v40, v46, v40
	v_fmac_f32_e32 v56, v42, v45
	v_mul_f32_e32 v42, v42, v44
	v_mov_b32_e32 v44, 1.0
	v_mov_b32_e32 v45, v145
	v_mov_b32_e32 v51, v145
	v_mov_b32_dpp v44, v40 row_shr:2 row_mask:0xf bank_mask:0xf
	v_mov_b32_dpp v45, v58 row_shr:2 row_mask:0xf bank_mask:0xf
	v_fmac_f32_e32 v58, v40, v45
	v_mul_f32_e32 v147, v40, v44
	v_mov_b32_e32 v40, 1.0
	v_mov_b32_e32 v44, v145
	s_waitcnt lgkmcnt(3)
	v_pk_fma_f32 v[38:39], v[80:81], v[86:87], v[140:141]
	v_mov_b32_dpp v40, v41 row_shr:2 row_mask:0xf bank_mask:0xf
	v_mul_f32_e32 v57, v41, v40
	v_mov_b32_e32 v40, 1.0
	v_mov_b32_dpp v44, v55 row_shr:2 row_mask:0xf bank_mask:0xf
	v_fmac_f32_e32 v55, v41, v44
	v_mov_b32_dpp v40, v43 row_shr:2 row_mask:0xf bank_mask:0xf
	v_mul_f32_e32 v59, v43, v40
	v_mov_b32_e32 v40, 1.0
	v_mov_b32_e32 v41, v145
	v_mov_b32_e32 v45, 1.0
	v_mov_b32_dpp v40, v42 row_shr:2 row_mask:0xf bank_mask:0xf
	v_mul_f32_e32 v60, v42, v40
	v_mov_b32_e32 v40, v145
	v_mov_b32_dpp v41, v54 row_shr:2 row_mask:0xf bank_mask:0xf
	v_fmac_f32_e32 v54, v43, v41
	v_mov_b32_dpp v40, v58 row_shr:4 row_mask:0xf bank_mask:0xf
	v_fmac_f32_e32 v58, v147, v40
	v_mov_b32_e32 v40, v145
	v_mov_b32_e32 v41, v145
	v_mov_b32_dpp v51, v58 row_shr:8 row_mask:0xf bank_mask:0xf
	v_mov_b32_dpp v40, v55 row_shr:4 row_mask:0xf bank_mask:0xf
	v_fmac_f32_e32 v55, v57, v40
	v_mov_b32_e32 v40, v145
	v_mov_b32_dpp v41, v56 row_shr:2 row_mask:0xf bank_mask:0xf
	v_fmac_f32_e32 v56, v42, v41
	v_mov_b32_dpp v40, v54 row_shr:4 row_mask:0xf bank_mask:0xf
	v_fmac_f32_e32 v54, v59, v40
	v_mov_b32_e32 v40, v145
	v_mov_b32_e32 v41, 1.0
	s_nop 0
	s_nop 0
	s_waitcnt vmcnt(6)
	v_lshlrev_b32_e32 v42, 16, v246
	v_mov_b32_dpp v40, v56 row_shr:4 row_mask:0xf bank_mask:0xf
	v_mov_b32_dpp v41, v147 row_shr:4 row_mask:0xf bank_mask:0xf
	v_fmac_f32_e32 v56, v60, v40
	v_lshlrev_b32_e32 v40, 16, v244
	v_mul_f32_e32 v42, 0xbfb8aa3b, v42
	v_exp_f32_e32 v50, v42
	v_pk_mul_f32 v[42:43], v[146:147], v[40:41]
	v_mul_f32_e32 v41, 0x3d372713, v40
	v_mul_f32_e32 v41, v41, v40
	v_fmac_f32_e32 v40, v41, v40
	v_mul_f32_e32 v40, 0x3f4c422a, v40
	v_add_f32_e32 v40, v40, v40
	v_mul_f32_e32 v40, 0x3fb8aa3b, v40
	v_exp_f32_e32 v40, v40
	v_add_f32_e32 v41, 1.0, v50
	v_rcp_f32_e32 v50, v41
	v_mov_b32_e32 v41, 1.0
	v_add_f32_e32 v40, 1.0, v40
	v_rcp_f32_e32 v40, v40
	v_mov_b32_dpp v41, v43 row_shr:8 row_mask:0xf bank_mask:0xf
	v_pk_mul_f32 v[34:35], v[82:83], v[86:87]
	v_mov_b32_dpp v45, v57 row_shr:4 row_mask:0xf bank_mask:0xf
	v_fma_f32 v40, v40, -2.0, 1.0
	v_add_f32_e32 v40, 1.0, v40
	v_and_b32_e32 v44, 0xffff0000, v244
	v_fmac_f32_e32 v58, v43, v51
	v_pk_mul_f32 v[52:53], v[42:43], v[40:41]
	v_mov_b32_e32 v51, v38
	v_mov_b32_e32 v147, v57
	ds_bpermute_b32 v40, v184, v53
	v_mul_f32_e32 v41, v34, v53
	v_pk_mul_f32 v[50:51], v[50:51], v[52:53]
	v_pk_mul_f32 v[52:53], v[146:147], v[44:45]
	v_mul_f32_e32 v45, 0x3d372713, v44
	v_mul_f32_e32 v45, v45, v44
	v_fmac_f32_e32 v44, v45, v44
	v_and_b32_e32 v64, 0xffff0000, v246
	v_add_f32_e32 v43, v51, v58
	v_mul_f32_e32 v44, 0x3f4c422a, v44
	ds_bpermute_b32 v42, v184, v58
	v_mul_f32_e32 v58, v50, v43
	v_mul_f32_e32 v43, 0xbfb8aa3b, v64
	v_add_f32_e32 v44, v44, v44
	v_exp_f32_e32 v43, v43
	v_mul_f32_e32 v44, 0x3fb8aa3b, v44
	v_exp_f32_e32 v45, v44
	v_mul_f32_e32 v57, v50, v41
	v_add_f32_e32 v41, 1.0, v43
	v_rcp_f32_e32 v44, v41
	v_add_f32_e32 v41, 1.0, v45
	v_rcp_f32_e32 v41, v41
	v_mov_b32_e32 v51, 1.0
	v_mov_b32_e32 v47, 1.0
	v_lshlrev_b32_e32 v46, 16, v245
	v_fma_f32 v41, v41, -2.0, 1.0
	v_mov_b32_dpp v51, v53 row_shr:8 row_mask:0xf bank_mask:0xf
	v_add_f32_e32 v50, 1.0, v41
	v_mov_b32_dpp v47, v59 row_shr:4 row_mask:0xf bank_mask:0xf
	v_pk_mul_f32 v[50:51], v[52:53], v[50:51]
	v_mov_b32_e32 v45, v39
	v_mov_b32_e32 v147, v59
	v_mov_b32_e32 v61, v145
	ds_bpermute_b32 v41, v184, v51
	v_mul_f32_e32 v52, v35, v51
	v_pk_mul_f32 v[44:45], v[44:45], v[50:51]
	v_pk_mul_f32 v[50:51], v[146:147], v[46:47]
	v_mul_f32_e32 v47, 0x3d372713, v46
	v_mov_b32_dpp v61, v55 row_shr:8 row_mask:0xf bank_mask:0xf
	v_mul_f32_e32 v47, v47, v46
	v_fmac_f32_e32 v55, v53, v61
	v_fmac_f32_e32 v46, v47, v46
	v_lshlrev_b32_e32 v65, 16, v247
	v_add_f32_e32 v45, v45, v55
	v_mul_f32_e32 v46, 0x3f4c422a, v46
	ds_bpermute_b32 v43, v184, v55
	v_mul_f32_e32 v55, v44, v45
	v_mul_f32_e32 v45, 0xbfb8aa3b, v65
	v_add_f32_e32 v46, v46, v46
	v_exp_f32_e32 v45, v45
	v_mul_f32_e32 v46, 0x3fb8aa3b, v46
	v_exp_f32_e32 v46, v46
	v_mul_f32_e32 v59, v44, v52
	v_add_f32_e32 v44, 1.0, v45
	v_rcp_f32_e32 v52, v44
	v_add_f32_e32 v44, 1.0, v46
	v_rcp_f32_e32 v44, v44
	v_mov_b32_e32 v62, v145
	v_mov_b32_e32 v45, 1.0
	s_waitcnt lgkmcnt(4)
	v_pk_fma_f32 v[36:37], v[76:77], v[142:143], v[162:163]
	v_fma_f32 v44, v44, -2.0, 1.0
	v_mov_b32_e32 v49, 1.0
	v_mov_b32_dpp v62, v54 row_shr:8 row_mask:0xf bank_mask:0xf
	v_mov_b32_dpp v45, v51 row_shr:8 row_mask:0xf bank_mask:0xf
	v_add_f32_e32 v44, 1.0, v44
	v_pk_mul_f32 v[32:33], v[78:79], v[142:143]
	v_mov_b32_dpp v49, v60 row_shr:4 row_mask:0xf bank_mask:0xf
	v_and_b32_e32 v48, 0xffff0000, v245
	v_fmac_f32_e32 v54, v51, v62
	v_pk_mul_f32 v[50:51], v[50:51], v[44:45]
	v_mov_b32_e32 v53, v36
	v_mov_b32_e32 v147, v60
	ds_bpermute_b32 v44, v184, v51
	v_mul_f32_e32 v45, v32, v51
	v_pk_mul_f32 v[50:51], v[52:53], v[50:51]
	v_pk_mul_f32 v[52:53], v[146:147], v[48:49]
	v_mul_f32_e32 v49, 0x3d372713, v48
	v_mul_f32_e32 v49, v49, v48
	v_fmac_f32_e32 v48, v49, v48
	v_and_b32_e32 v66, 0xffff0000, v247
	v_add_f32_e32 v47, v51, v54
	v_mul_f32_e32 v48, 0x3f4c422a, v48
	ds_bpermute_b32 v46, v184, v54
	v_mul_f32_e32 v54, v50, v47
	v_mul_f32_e32 v47, 0xbfb8aa3b, v66
	v_add_f32_e32 v48, v48, v48
	v_exp_f32_e32 v47, v47
	v_mul_f32_e32 v48, 0x3fb8aa3b, v48
	v_exp_f32_e32 v49, v48
	v_mul_f32_e32 v60, v50, v45
	v_add_f32_e32 v45, 1.0, v47
	v_rcp_f32_e32 v48, v45
	v_add_f32_e32 v45, 1.0, v49
	v_rcp_f32_e32 v45, v45
	v_mov_b32_e32 v63, v145
	v_mov_b32_e32 v51, 1.0
	v_mov_b32_e32 v49, v37
	v_fma_f32 v45, v45, -2.0, 1.0
	v_mov_b32_dpp v63, v56 row_shr:8 row_mask:0xf bank_mask:0xf
	v_mov_b32_dpp v51, v53 row_shr:8 row_mask:0xf bank_mask:0xf
	v_add_f32_e32 v50, 1.0, v45
	v_fmac_f32_e32 v56, v53, v63
	v_pk_mul_f32 v[50:51], v[52:53], v[50:51]
	ds_bpermute_b32 v45, v184, v51
	ds_bpermute_b32 v47, v184, v56
	v_pk_mul_f32 v[48:49], v[48:49], v[50:51]
	s_mov_b32 s54, 0x25d59000
	v_add_f32_e32 v49, v49, v56
	v_add_co_u32_e32 v50, vcc, s54, v84
	v_mul_f32_e32 v52, v33, v51
	v_mul_f32_e32 v49, v48, v49
	v_addc_co_u32_e32 v51, vcc, 0, v85, vcc
	v_mul_f32_e32 v52, v48, v52
	v_cvt_pk_bf16_f32 v48, v58, v55
	v_cvt_pk_bf16_f32 v49, v54, v49
	global_store_dwordx2 v[50:51], v[48:49], off
	v_add_co_u32_e32 v50, vcc, 0x27d59000, v84
	v_cvt_pk_bf16_f32 v48, v57, v59
	v_cvt_pk_bf16_f32 v49, v60, v52
	s_nop 1
	v_addc_co_u32_e32 v51, vcc, 0, v85, vcc
	global_store_dwordx2 v[50:51], v[48:49], off
	s_and_saveexec_b64 s[54:55], s[6:7]
	s_cbranch_execz .LBB0_194
	s_waitcnt lgkmcnt(0)
	v_pk_fma_f32 v[48:49], v[36:37], v[44:45], v[46:47]
	v_pk_mul_f32 v[36:37], v[32:33], v[44:45]
	v_lshl_add_u64 v[32:33], s[74:75], 0, v[130:131]
	v_pk_fma_f32 v[46:47], v[38:39], v[40:41], v[42:43]
	v_add_co_u32_e32 v38, vcc, 0x2dd41000, v32
	v_pk_mul_f32 v[34:35], v[34:35], v[40:41]
	s_nop 0
	v_addc_co_u32_e32 v39, vcc, 0, v33, vcc
	v_add_co_u32_e32 v32, vcc, 0x2de41000, v32
	global_store_dwordx4 v[38:39], v[34:37], off
	s_nop 0
	v_addc_co_u32_e32 v33, vcc, 0, v33, vcc
	global_store_dwordx4 v[32:33], v[46:49], off
	s_branch .LBB0_194
